# LRU gate stage: the 31 per-block parameter / u LDS reads issued together right after the gate GEMM into registers the fragment ring released, one wait, per-block waits dropped
# speedup vs baseline: 1.0203x; 1.0098x over previous
; DEVI unsigned pk2(float lo, float hi) { f32x2 v = {lo, hi}; bf16x2_t b = __builtin_convertvector(v, bf16x2_t); return __builtin_bit_cast(unsigned, b); }
; DEVI float bflo(unsigned u) { return __uint_as_float(u << 16); }
; DEVI float bfhi(unsigned u) { return __uint_as_float(u & 0xffff0000u); }
; template <bool PASS_C>
; DEVI void lru_item(const P& p, int item, int next_item, uint4& u0, uint4& u1, uint4& u2, float& cpre, char* smem) {
;     ...
;     {
;         const int tok = tid >> 2, cg0 = (tid & 3) * 16;
;         uint4 r[4][2];
; #pragma unroll
;         for (int k = 0; k < 4; ++k) { r[k][0] = *(const uint4*)(us + (tok + k) * 64 + cg0); r[k][1] = *(const uint4*)(us + (tok + k) * 64 + cg0 + 8); }
;         float val[16];
; #pragma unroll
;         for (int e = 0; e < 16; ++e) {
;             const int ch = cg0 + e;
;             float a = prm[4 * 64 + ch];
; #pragma unroll
;             for (int k = 0; k < 4; ++k) {
;                 const uint4 q = r[k][e >> 3];
;                 const unsigned wd = ((e >> 1) & 3) == 0 ? q.x : (((e >> 1) & 3) == 1 ? q.y : (((e >> 1) & 3) == 2 ? q.z : q.w));
;                 a += prm[k * 64 + ch] * ((e & 1) ? bfhi(wd) : bflo(wd));
;             }
;             val[e] = a;
;         }
;         uint4 o;
;         o.x = pk2(val[0], val[1]); o.y = pk2(val[2], val[3]); o.z = pk2(val[4], val[5]); o.w = pk2(val[6], val[7]);
;         *(uint4*)(ucb + tok * 128 + ((((cg0 >> 3) + 0) ^ (tok & 7)) << 4)) = o;
;         o.x = pk2(val[8], val[9]); o.y = pk2(val[10], val[11]); o.z = pk2(val[12], val[13]); o.w = pk2(val[14], val[15]);
;         *(uint4*)(ucb + tok * 128 + ((((cg0 >> 3) + 1) ^ (tok & 7)) << 4)) = o;
;     }
.LBB0_510:
	s_waitcnt lgkmcnt(0)
	s_barrier
	ds_read_b128 v[32:35], v118 offset:35840
	ds_read_b128 v[12:15], v118 offset:35856
	ds_read_b128 v[36:39], v118 offset:35968
	ds_read_b128 v[16:19], v118 offset:35984
	ds_read_b128 v[40:43], v118 offset:36096
	ds_read_b128 v[20:23], v118 offset:36112
	ds_read_b128 v[44:47], v118 offset:36224
	ds_read_b128 v[24:27], v118 offset:36240
	ds_read_b128 v[48:51], v111 offset:33792
	ds_read_b128 v[52:55], v111 offset:32768
	ds_read_b128 v[56:59], v111 offset:32784
	ds_read_b128 v[60:63], v111 offset:32800
	ds_read_b128 v[28:31], v111 offset:32816
	ds_read_b128 v[64:67], v111 offset:33024
	ds_read_b128 v[92:95], v111 offset:33808
	s_waitcnt lgkmcnt(14)
	v_lshlrev_b32_e32 v96, 16, v32
	v_and_b32_e32 v97, 0xffff0000, v32
	s_waitcnt lgkmcnt(5)
	v_pk_fma_f32 v[48:49], v[52:53], v[96:97], v[48:49]
	ds_read_b128 v[96:99], v111 offset:33280
	ds_read_b128 v[146:149], v111 offset:33536
	ds_read_b128 v[150:153], v111 offset:33040
	v_lshlrev_b32_e32 v32, 16, v33
	v_and_b32_e32 v33, 0xffff0000, v33
	v_lshlrev_b32_e32 v154, 16, v36
	v_and_b32_e32 v155, 0xffff0000, v36
	v_lshlrev_b32_e32 v36, 16, v37
	v_and_b32_e32 v37, 0xffff0000, v37
	v_pk_fma_f32 v[32:33], v[54:55], v[32:33], v[50:51]
	v_lshlrev_b32_e32 v158, 16, v40
	v_and_b32_e32 v159, 0xffff0000, v40
	s_waitcnt lgkmcnt(4)
	v_pk_fma_f32 v[48:49], v[64:65], v[154:155], v[48:49]
	ds_read_b128 v[154:157], v111 offset:33296
	v_lshlrev_b32_e32 v40, 16, v41
	v_and_b32_e32 v41, 0xffff0000, v41
	v_pk_fma_f32 v[32:33], v[66:67], v[36:37], v[32:33]
	v_lshlrev_b32_e32 v162, 16, v44
	v_and_b32_e32 v163, 0xffff0000, v44
	s_waitcnt lgkmcnt(3)
	v_pk_fma_f32 v[48:49], v[96:97], v[158:159], v[48:49]
	ds_read_b128 v[158:161], v111 offset:33552
	v_lshlrev_b32_e32 v44, 16, v45
	v_and_b32_e32 v45, 0xffff0000, v45
	v_pk_fma_f32 v[32:33], v[98:99], v[40:41], v[32:33]
	v_lshlrev_b32_e32 v36, 16, v38
	s_waitcnt lgkmcnt(3)
	v_pk_fma_f32 v[98:99], v[148:149], v[44:45], v[32:33]
	v_lshlrev_b32_e32 v32, 16, v34
	v_and_b32_e32 v33, 0xffff0000, v34
	v_and_b32_e32 v37, 0xffff0000, v38
	v_pk_fma_f32 v[32:33], v[56:57], v[32:33], v[92:93]
	v_lshlrev_b32_e32 v40, 16, v42
	v_and_b32_e32 v41, 0xffff0000, v42
	s_waitcnt lgkmcnt(2)
	v_pk_fma_f32 v[32:33], v[150:151], v[36:37], v[32:33]
	v_lshlrev_b32_e32 v44, 16, v46
	v_and_b32_e32 v45, 0xffff0000, v46
	s_waitcnt lgkmcnt(1)
	v_pk_fma_f32 v[32:33], v[154:155], v[40:41], v[32:33]
	v_lshlrev_b32_e32 v34, 16, v39
	s_waitcnt lgkmcnt(0)
	v_pk_fma_f32 v[92:93], v[158:159], v[44:45], v[32:33]
	v_lshlrev_b32_e32 v32, 16, v35
	v_and_b32_e32 v33, 0xffff0000, v35
	v_and_b32_e32 v35, 0xffff0000, v39
	v_pk_fma_f32 v[32:33], v[58:59], v[32:33], v[94:95]
	v_lshlrev_b32_e32 v36, 16, v43
	v_and_b32_e32 v37, 0xffff0000, v43
	v_pk_fma_f32 v[32:33], v[152:153], v[34:35], v[32:33]
	v_lshlrev_b32_e32 v38, 16, v47
	v_and_b32_e32 v39, 0xffff0000, v47
	v_pk_fma_f32 v[32:33], v[156:157], v[36:37], v[32:33]
	v_lshlrev_b32_e32 v44, 16, v12
	v_pk_fma_f32 v[94:95], v[160:161], v[38:39], v[32:33]
	ds_read_b128 v[32:35], v111 offset:33824
	ds_read_b128 v[36:39], v111 offset:33056
	ds_read_b128 v[40:43], v111 offset:33840
	v_and_b32_e32 v45, 0xffff0000, v12
	v_pk_fma_f32 v[96:97], v[146:147], v[162:163], v[48:49]
	v_lshlrev_b32_e32 v12, 16, v13
	s_waitcnt lgkmcnt(2)
	v_pk_fma_f32 v[32:33], v[60:61], v[44:45], v[32:33]
	ds_read_b128 v[44:47], v111 offset:33312
	ds_read_b128 v[48:51], v111 offset:33568
	ds_read_b128 v[52:55], v111 offset:33072
	v_and_b32_e32 v13, 0xffff0000, v13
	v_lshlrev_b32_e32 v56, 16, v16
	v_and_b32_e32 v57, 0xffff0000, v16
	v_lshlrev_b32_e32 v16, 16, v17
	v_and_b32_e32 v17, 0xffff0000, v17
	v_pk_fma_f32 v[12:13], v[62:63], v[12:13], v[34:35]
	v_lshlrev_b32_e32 v64, 16, v20
	v_and_b32_e32 v65, 0xffff0000, v20
	s_waitcnt lgkmcnt(4)
	v_pk_fma_f32 v[32:33], v[36:37], v[56:57], v[32:33]
	ds_read_b128 v[56:59], v111 offset:33328
	v_lshlrev_b32_e32 v20, 16, v21
	v_and_b32_e32 v21, 0xffff0000, v21
	v_pk_fma_f32 v[12:13], v[38:39], v[16:17], v[12:13]
	v_lshlrev_b32_e32 v146, 16, v24
	v_and_b32_e32 v147, 0xffff0000, v24
	s_waitcnt lgkmcnt(3)
	v_pk_fma_f32 v[32:33], v[44:45], v[64:65], v[32:33]
	ds_read_b128 v[64:67], v111 offset:33584
	v_lshlrev_b32_e32 v24, 16, v25
	v_and_b32_e32 v25, 0xffff0000, v25
	v_pk_fma_f32 v[12:13], v[46:47], v[20:21], v[12:13]
	v_lshlrev_b32_e32 v20, 16, v18
	s_waitcnt lgkmcnt(3)
	v_pk_fma_f32 v[16:17], v[50:51], v[24:25], v[12:13]
	v_lshlrev_b32_e32 v12, 16, v14
	v_and_b32_e32 v13, 0xffff0000, v14
	v_and_b32_e32 v21, 0xffff0000, v18
	v_pk_fma_f32 v[12:13], v[28:29], v[12:13], v[40:41]
	v_lshlrev_b32_e32 v24, 16, v22
	v_and_b32_e32 v25, 0xffff0000, v22
	s_waitcnt lgkmcnt(2)
	v_pk_fma_f32 v[12:13], v[52:53], v[20:21], v[12:13]
	v_lshlrev_b32_e32 v34, 16, v26
	v_and_b32_e32 v35, 0xffff0000, v26
	s_waitcnt lgkmcnt(1)
	v_pk_fma_f32 v[12:13], v[56:57], v[24:25], v[12:13]
	v_lshlrev_b32_e32 v14, 16, v19
	s_waitcnt lgkmcnt(0)
	v_pk_fma_f32 v[20:21], v[64:65], v[34:35], v[12:13]
	v_lshlrev_b32_e32 v12, 16, v15
	v_and_b32_e32 v13, 0xffff0000, v15
	v_and_b32_e32 v15, 0xffff0000, v19
	v_pk_fma_f32 v[12:13], v[30:31], v[12:13], v[42:43]
	v_lshlrev_b32_e32 v18, 16, v23
	v_and_b32_e32 v19, 0xffff0000, v23
	v_pk_fma_f32 v[12:13], v[54:55], v[14:15], v[12:13]
	v_lshlrev_b32_e32 v22, 16, v27
	v_and_b32_e32 v23, 0xffff0000, v27
	v_pk_fma_f32 v[12:13], v[58:59], v[18:19], v[12:13]
	v_pk_fma_f32 v[32:33], v[48:49], v[146:147], v[32:33]
	v_pk_fma_f32 v[18:19], v[66:67], v[22:23], v[12:13]
	v_cvt_pk_bf16_f32 v12, v96, v97
	v_cvt_pk_bf16_f32 v13, v98, v99
	v_cvt_pk_bf16_f32 v14, v92, v93
	v_cvt_pk_bf16_f32 v15, v94, v95
	ds_write_b128 v119, v[12:15] offset:44544
	v_cvt_pk_bf16_f32 v12, v32, v33
	v_cvt_pk_bf16_f32 v13, v16, v17
	v_cvt_pk_bf16_f32 v14, v20, v21
	v_cvt_pk_bf16_f32 v15, v18, v19
	ds_write_b128 v120, v[12:15] offset:44544
	v_add_u32_e32 v12, v113, v114
	s_waitcnt lgkmcnt(0)
	s_barrier
; DEVI float bf2f(bf16_t h) { return __uint_as_float(((unsigned)h) << 16); }
; template <bool PASS_C>
; DEVI void lru_item(const P& p, int item, int next_item, uint4& u0, uint4& u1, uint4& u2, float& cpre, char* smem) {
;     ...
;     f32x4 acc[16];
; #pragma unroll
;     for (int n = 0; n < 16; ++n) acc[n] = (f32x4){0.f, 0.f, 0.f, 0.f};
;     {
;         bf16x8 af[2];
; #pragma unroll
;         for (int kk = 0; kk < 2; ++kk) af[kk] = *(const bf16x8*)(ucb + (16 * w + fr) * 128 + (((kk * 4 + fq) ^ (fr & 7)) << 4));
; #pragma unroll
;         for (int n = 0; n < 16; ++n)
; #pragma unroll
;             for (int kk = 0; kk < 2; ++kk) {
;                 const bf16x8 bfr = *(const bf16x8*)(smem + (16 * n + fr) * 128 + (((kk * 4 + fq) ^ (fr & 7)) << 4));
;                 acc[n] = __builtin_amdgcn_mfma_f32_16x16x32_bf16(af[kk], bfr, acc[n], 0, 0, 0);
;             }
;     }
;     float av[4][2][4], bv[4][2][4], apre[4][2], bpre[4][2];
; #pragma unroll
;     for (int nn = 0; nn < 4; ++nn) {
;         const int ch = 16 * nn + fr;
;         float uc[4];
; #pragma unroll
;         for (int j = 0; j < 4; ++j) {
;             const int tl = 16 * w + 4 * fq + j;
;             uc[j] = bf2f(*(const bf16_t*)(ucb + tl * 128 + ((((ch >> 3)) ^ (tl & 7)) << 4) + (ch & 7) * 2));
;         }
; #pragma unroll
;         for (int d = 0; d < 2; ++d) {
;             const float ba = prm[(5 + d) * 64 + ch], bx = prm[(7 + d) * 64 + ch], nsp8 = prm[(9 + d) * 64 + ch];
	v_add_u32_e32 v75, v112, v114
	v_add_u32_e32 v20, v113, v115
	v_add_u32_e32 v77, v112, v115
	ds_read_b128 v[12:15], v12 offset:44544
	ds_read_b128 v[92:95], v20 offset:44544
	ds_read_b32 v83, v116 offset:35072
	ds_read_b128 v[232:235], v75
	ds_read_b128 v[236:239], v77
	ds_read_b128 v[240:243], v75 offset:2048
	ds_read_b128 v[244:247], v77 offset:2048
	ds_read_b128 v[248:251], v75 offset:4096
	ds_read_b128 v[158:161], v77 offset:4096
	ds_read_b128 v[252:255], v75 offset:6144
	ds_read_b128 v[218:221], v77 offset:6144
	s_waitcnt lgkmcnt(4)
	v_mfma_f32_16x16x32_bf16 v[146:149], v[12:15], v[232:235], 0
	ds_read_b128 v[222:225], v75 offset:8192
	ds_read_b128 v[226:229], v77 offset:8192
	ds_read_b128 v[96:99], v75 offset:10240
	ds_read_b128 v[154:157], v77 offset:10240
	v_mfma_f32_16x16x32_bf16 v[56:59], v[12:15], v[240:243], 0
	v_mfma_f32_16x16x32_bf16 v[146:149], v[92:95], v[236:239], v[146:149]
	v_mfma_f32_16x16x32_bf16 v[56:59], v[92:95], v[244:247], v[56:59]
	s_waitcnt lgkmcnt(4)
	v_mfma_f32_16x16x32_bf16 v[40:43], v[12:15], v[248:251], 0
	ds_read_b128 v[232:235], v75 offset:12288
	ds_read_b128 v[236:239], v77 offset:12288
	ds_read_b128 v[240:243], v75 offset:14336
	ds_read_b128 v[244:247], v77 offset:14336
	v_mfma_f32_16x16x32_bf16 v[24:27], v[12:15], v[252:255], 0
	v_mfma_f32_16x16x32_bf16 v[40:43], v[92:95], v[158:161], v[40:43]
	v_mfma_f32_16x16x32_bf16 v[24:27], v[92:95], v[218:221], v[24:27]
	s_waitcnt lgkmcnt(4)
	v_mfma_f32_16x16x32_bf16 v[150:153], v[12:15], v[222:225], 0
	ds_read_b128 v[248:251], v75 offset:16384
	ds_read_b128 v[158:161], v77 offset:16384
	ds_read_b128 v[252:255], v75 offset:18432
	ds_read_b128 v[218:221], v77 offset:18432
	v_mfma_f32_16x16x32_bf16 v[52:55], v[12:15], v[96:99], 0
	v_mfma_f32_16x16x32_bf16 v[150:153], v[92:95], v[226:229], v[150:153]
	v_mfma_f32_16x16x32_bf16 v[52:55], v[92:95], v[154:157], v[52:55]
	s_waitcnt lgkmcnt(4)
	v_mfma_f32_16x16x32_bf16 v[36:39], v[12:15], v[232:235], 0
	ds_read_b128 v[222:225], v75 offset:20480
	ds_read_b128 v[226:229], v77 offset:20480
	ds_read_b128 v[96:99], v75 offset:22528
	ds_read_b128 v[154:157], v77 offset:22528
	v_mfma_f32_16x16x32_bf16 v[20:23], v[12:15], v[240:243], 0
	v_mfma_f32_16x16x32_bf16 v[36:39], v[92:95], v[236:239], v[36:39]
	v_mfma_f32_16x16x32_bf16 v[20:23], v[92:95], v[244:247], v[20:23]
	s_waitcnt lgkmcnt(4)
	v_mfma_f32_16x16x32_bf16 v[64:67], v[12:15], v[248:251], 0
	ds_read_b128 v[232:235], v75 offset:24576
	ds_read_b128 v[236:239], v77 offset:24576
	ds_read_b128 v[240:243], v75 offset:26624
	ds_read_b128 v[244:247], v77 offset:26624
	v_mfma_f32_16x16x32_bf16 v[48:51], v[12:15], v[252:255], 0
	v_mfma_f32_16x16x32_bf16 v[64:67], v[92:95], v[158:161], v[64:67]
	v_mfma_f32_16x16x32_bf16 v[48:51], v[92:95], v[218:221], v[48:51]
	s_waitcnt lgkmcnt(4)
	v_mfma_f32_16x16x32_bf16 v[32:35], v[12:15], v[222:225], 0
	ds_read_b128 v[248:251], v75 offset:28672
	ds_read_b128 v[252:255], v75 offset:30720
	ds_read_b128 v[158:161], v77 offset:28672
	v_mfma_f32_16x16x32_bf16 v[16:19], v[12:15], v[96:99], 0
	v_mfma_f32_16x16x32_bf16 v[32:35], v[92:95], v[226:229], v[32:35]
	v_mfma_f32_16x16x32_bf16 v[16:19], v[92:95], v[154:157], v[16:19]
	s_waitcnt lgkmcnt(3)
	v_mfma_f32_16x16x32_bf16 v[60:63], v[12:15], v[232:235], 0
	v_mfma_f32_16x16x32_bf16 v[44:47], v[12:15], v[240:243], 0
	v_mfma_f32_16x16x32_bf16 v[60:63], v[92:95], v[236:239], v[60:63]
	v_mfma_f32_16x16x32_bf16 v[44:47], v[92:95], v[244:247], v[44:47]
	s_waitcnt lgkmcnt(1)
	v_mfma_f32_16x16x32_bf16 v[28:31], v[12:15], v[248:251], 0
	v_mfma_f32_16x16x32_bf16 v[12:15], v[12:15], v[252:255], 0
	ds_read_b128 v[96:99], v77 offset:30720
	ds_read2st64_b32 v[154:155], v116 offset0:133 offset1:135
	ds_read_u16 v246, v121 offset:44544
	ds_read_u16 v247, v122 offset:44544
	ds_read_u16 v248, v123 offset:44544
	ds_read_u16 v249, v124 offset:44544
	ds_read2st64_b32 v[232:233], v116 offset0:134 offset1:136
	ds_read_b32 v250, v116 offset:35328
	v_add_u32_e32 v217, 64, v116
	ds_read2st64_b32 v[234:235], v217 offset0:133 offset1:135
	ds_read_u16 v251, v125 offset:44544
	ds_read_u16 v252, v126 offset:44544
	ds_read_u16 v253, v127 offset:44544
	ds_read_u16 v254, v128 offset:44544
	ds_read_b32 v255, v116 offset:35136
	v_add_u32_e32 v217, 64, v116
	ds_read2st64_b32 v[236:237], v217 offset0:134 offset1:136
	ds_read_b32 v218, v116 offset:35392
	v_add_u32_e32 v217, 0x80, v116
	ds_read2st64_b32 v[238:239], v217 offset0:133 offset1:135
	ds_read_u16 v219, v129 offset:44544
	ds_read_u16 v220, v130 offset:44544
	ds_read_u16 v221, v131 offset:44544
	ds_read_u16 v222, v132 offset:44544
	ds_read_b32 v223, v116 offset:35200
	v_add_u32_e32 v217, 0x80, v116
	ds_read2st64_b32 v[240:241], v217 offset0:134 offset1:136
	ds_read_b32 v224, v116 offset:35456
	v_add_u32_e32 v217, 0xc0, v116
	ds_read2st64_b32 v[242:243], v217 offset0:133 offset1:135
	ds_read_u16 v225, v133 offset:44544
	ds_read_u16 v226, v134 offset:44544
	ds_read_u16 v227, v135 offset:44544
	ds_read_u16 v228, v136 offset:44544
	ds_read_b32 v229, v116 offset:35264
	v_add_u32_e32 v217, 0xc0, v116
	ds_read2st64_b32 v[244:245], v217 offset0:134 offset1:136
	ds_read_b32 v231, v116 offset:35520
	s_waitcnt lgkmcnt(0)
; template <bool PASS_C>
; DEVI void lru_item(const P& p, int item, int next_item, uint4& u0, uint4& u1, uint4& u2, float& cpre, char* smem) {
;     ...
;         for (int d = 0; d < 2; ++d) {
;             const float ba = prm[(5 + d) * 64 + ch], bx = prm[(7 + d) * 64 + ch], nsp8 = prm[(9 + d) * 64 + ch];
; #pragma unroll
;             for (int j = 0; j < 4; ++j) {
;                 const float r = __builtin_amdgcn_rcpf(1.0f + __builtin_amdgcn_exp2f(__builtin_fmaf(acc[(2 * d) * 4 + nn][j], -LOG2E, ba)));
;                 const float ig = __builtin_amdgcn_rcpf(1.0f + __builtin_amdgcn_exp2f(__builtin_fmaf(acc[(2 * d + 1) * 4 + nn][j], -LOG2E, bx)));
;                 const float a_ = __builtin_amdgcn_exp2f(nsp8 * r);
;                 av[nn][d][j] = a_;
;                 bv[nn][d][j] = __builtin_amdgcn_sqrtf(__builtin_fmaf(-a_, a_, 1.0f)) * ig * uc[j];
;             }
;             float A = 1.f, Bq = 0.f;
;             if (d == 0) {
; #pragma unroll
;                 for (int j = 0; j < 4; ++j) { Bq = av[nn][d][j] * Bq + bv[nn][d][j]; A *= av[nn][d][j]; }
;             } else {
; #pragma unroll
;                 for (int j = 3; j >= 0; --j) { Bq = av[nn][d][j] * Bq + bv[nn][d][j]; A *= av[nn][d][j]; }
;             }
;             float Ag[4], Bg[4];
;             rowgather4(A, Ag); rowgather4(Bq, Bg);
;             float AW = 1.f, BW = 0.f, AP = 1.f, BP = 0.f;
;             if (d == 0) {
; #pragma unroll
;                 for (int g = 0; g < 4; ++g) {
;                     if (g == fq) { AP = AW; BP = BW; }
;                     BW = Ag[g] * BW + Bg[g]; AW *= Ag[g];
;                 }
;             } else {
; #pragma unroll
;                 for (int g = 3; g >= 0; --g) {
;                     if (g == fq) { AP = AW; BP = BW; }
;                     BW = Ag[g] * BW + Bg[g]; AW *= Ag[g];
;                 }
;             }
;             apre[nn][d] = AP; bpre[nn][d] = BP;
;             if (fq == 0) { wagg[((w * 2 + d) * 64 + ch) * 2 + 0] = AW; wagg[((w * 2 + d) * 64 + ch) * 2 + 1] = BW; }
;         }
	v_fmamk_f32 v81, v146, 0xbfb8aa3b, v154
	v_exp_f32_e32 v81, v81
	v_fmamk_f32 v91, v149, 0xbfb8aa3b, v154
	v_exp_f32_e32 v91, v91
	v_mfma_f32_16x16x32_bf16 v[28:31], v[92:95], v[158:161], v[28:31]
	v_add_f32_e32 v81, 1.0, v81
	v_rcp_f32_e32 v87, v81
	v_fmamk_f32 v81, v147, 0xbfb8aa3b, v154
	v_exp_f32_e32 v89, v81
	v_lshlrev_b32_e32 v81, 16, v249
	v_mul_f32_e32 v85, v83, v87
	v_mfma_f32_16x16x32_bf16 v[12:15], v[92:95], v[96:99], v[12:15]
	v_add_f32_e32 v87, 1.0, v89
	v_fmamk_f32 v89, v148, 0xbfb8aa3b, v154
	v_exp_f32_e32 v89, v89
	v_add_f32_e32 v91, 1.0, v91
	v_fmamk_f32 v93, v150, 0xbfb8aa3b, v155
	v_rcp_f32_e32 v87, v87
	v_add_f32_e32 v89, 1.0, v89
	v_exp_f32_e32 v85, v85
	v_rcp_f32_e32 v89, v89
	v_rcp_f32_e32 v91, v91
	v_exp_f32_e32 v93, v93
	v_mul_f32_e32 v87, v83, v87
	v_mul_f32_e32 v89, v83, v89
	v_mul_f32_e32 v83, v83, v91
	v_add_f32_e32 v91, 1.0, v93
	v_fma_f32 v93, -v85, v85, 1.0
	v_rcp_f32_e32 v91, v91
	v_sqrt_f32_e32 v93, v93
	v_fmamk_f32 v94, v151, 0xbfb8aa3b, v155
	v_exp_f32_e32 v87, v87
	v_exp_f32_e32 v94, v94
	v_lshlrev_b32_e32 v75, 16, v246
	v_mul_f32_e32 v91, v91, v93
	v_mul_f32_e32 v91, v91, v75
	v_mul_f32_e32 v92, v85, v87
	v_fmac_f32_e32 v91, 0, v85
	v_add_f32_e32 v85, 1.0, v94
	v_fma_f32 v93, -v87, v87, 1.0
	v_rcp_f32_e32 v85, v85
	v_sqrt_f32_e32 v93, v93
	v_mul_f32_e32 v87, v87, v91
	v_fmamk_f32 v91, v152, 0xbfb8aa3b, v155
	v_exp_f32_e32 v89, v89
	v_exp_f32_e32 v91, v91
	v_lshlrev_b32_e32 v77, 16, v247
	v_mul_f32_e32 v85, v85, v93
	v_fmac_f32_e32 v87, v85, v77
	v_fmamk_f32 v155, v153, 0xbfb8aa3b, v155
	v_exp_f32_e32 v83, v83
	v_mul_f32_e32 v85, v89, v87
	v_add_f32_e32 v87, 1.0, v91
	v_exp_f32_e32 v91, v155
	v_mul_f32_e32 v92, v89, v92
	v_fma_f32 v89, -v89, v89, 1.0
	v_rcp_f32_e32 v87, v87
	v_sqrt_f32_e32 v89, v89
	v_add_f32_e32 v91, 1.0, v91
	v_fma_f32 v93, -v83, v83, 1.0
	v_rcp_f32_e32 v91, v91
	v_sqrt_f32_e32 v93, v93
	v_lshlrev_b32_e32 v79, 16, v248
	v_mul_f32_e32 v87, v87, v89
	v_fmac_f32_e32 v85, v87, v79
	v_mul_f32_e32 v92, v83, v92
	v_mul_f32_e32 v83, v83, v85
	v_mul_f32_e32 v85, v91, v93
	v_fmac_f32_e32 v83, v85, v81
	v_mov_b32_e32 v96, v92
	v_mov_b32_e32 v85, v83
	s_nop 0
	v_permlane16_swap_b32_e32 v92, v96
	v_permlane16_swap_b32_e32 v83, v85
	v_mov_b32_e32 v94, v92
	v_mov_b32_e32 v95, v96
	v_mov_b32_e32 v97, v83
	v_mov_b32_e32 v99, v85
	v_permlane32_swap_b32_e32 v92, v94
	v_permlane32_swap_b32_e32 v96, v95
	v_permlane32_swap_b32_e32 v83, v97
	v_permlane32_swap_b32_e32 v85, v99
	s_and_saveexec_b64 s[12:13], s[8:9]
	s_cbranch_execz .LBB0_512
	v_fmac_f32_e32 v83, 0, v92
	v_fmac_f32_e32 v85, v83, v96
	v_mul_f32_e32 v93, v85, v94
	v_pk_mul_f32 v[146:147], v[92:93], v[96:97]
	v_pk_add_f32 v[92:93], v[92:93], v[96:97]
	v_mov_b32_e32 v96, v95
	v_mov_b32_e32 v92, v146
	v_mov_b32_e32 v98, v95
	v_pk_mul_f32 v[146:147], v[146:147], v[94:95]
	v_pk_fma_f32 v[92:93], v[92:93], v[94:95], v[98:99]
	v_pk_mul_f32 v[96:97], v[146:147], v[96:97]
	s_nop 0
	v_mov_b32_e32 v97, v93
	ds_write_b64 v141, v[96:97] offset:52736
.LBB0_512:
	s_or_b64 exec, exec, s[12:13]
	v_fmamk_f32 v67, v67, 0xbfb8aa3b, v232
	v_exp_f32_e32 v67, v67
	v_fmamk_f32 v66, v66, 0xbfb8aa3b, v232
	v_fmamk_f32 v65, v65, 0xbfb8aa3b, v232
	v_fmamk_f32 v64, v64, 0xbfb8aa3b, v232
	v_add_f32_e32 v67, 1.0, v67
	v_exp_f32_e32 v66, v66
	v_exp_f32_e32 v65, v65
	v_rcp_f32_e32 v67, v67
	v_exp_f32_e32 v64, v64
	v_fmamk_f32 v63, v63, 0xbfb8aa3b, v233
	v_add_f32_e32 v66, 1.0, v66
	v_add_f32_e32 v65, 1.0, v65
	v_mul_f32_e32 v67, v250, v67
	v_add_f32_e32 v64, 1.0, v64
	v_exp_f32_e32 v63, v63
	v_rcp_f32_e32 v66, v66
	v_exp_f32_e32 v67, v67
	v_rcp_f32_e32 v65, v65
	v_rcp_f32_e32 v64, v64
	v_add_f32_e32 v63, 1.0, v63
	v_mul_f32_e32 v66, v250, v66
	v_mul_f32_e32 v65, v250, v65
	v_mul_f32_e32 v64, v250, v64
	v_rcp_f32_e32 v83, v63
	v_fma_f32 v63, -v67, v67, 1.0
	v_sqrt_f32_e32 v87, v63
	v_fmamk_f32 v62, v62, 0xbfb8aa3b, v233
	v_exp_f32_e32 v66, v66
	v_exp_f32_e32 v62, v62
	v_mul_f32_e32 v83, v83, v87
	v_mul_f32_e32 v81, v83, v81
	v_mul_f32_e32 v85, v67, v66
	v_fmac_f32_e32 v81, 0, v67
	v_add_f32_e32 v62, 1.0, v62
	v_fma_f32 v67, -v66, v66, 1.0
	v_rcp_f32_e32 v62, v62
	v_sqrt_f32_e32 v67, v67
	v_fmamk_f32 v61, v61, 0xbfb8aa3b, v233
	v_exp_f32_e32 v65, v65
	v_exp_f32_e32 v61, v61
	v_fmamk_f32 v93, v60, 0xbfb8aa3b, v233
	v_exp_f32_e32 v64, v64
	v_mul_f32_e32 v66, v66, v81
	v_mul_f32_e32 v62, v62, v67
	v_exp_f32_e32 v60, v93
	v_fmac_f32_e32 v66, v62, v79
	v_mul_f32_e32 v85, v65, v85
	v_mul_f32_e32 v62, v65, v66
	v_add_f32_e32 v61, 1.0, v61
	v_fma_f32 v65, -v65, v65, 1.0
	v_rcp_f32_e32 v61, v61
	v_sqrt_f32_e32 v65, v65
	v_add_f32_e32 v60, 1.0, v60
	v_fma_f32 v66, -v64, v64, 1.0
	v_rcp_f32_e32 v60, v60
	v_sqrt_f32_e32 v66, v66
	v_mul_f32_e32 v61, v61, v65
	v_fmac_f32_e32 v62, v61, v77
	v_mul_f32_e32 v61, v64, v62
	v_mul_f32_e32 v60, v60, v66
	v_mul_f32_e32 v63, v64, v85
	v_fmac_f32_e32 v61, v60, v75
	v_mov_b32_e32 v62, v63
	v_mov_b32_e32 v67, v61
	s_nop 0
	v_permlane16_swap_b32_e32 v63, v62
	v_permlane16_swap_b32_e32 v61, v67
	v_mov_b32_e32 v64, v63
	v_mov_b32_e32 v66, v62
	v_mov_b32_e32 v60, v61
	v_mov_b32_e32 v65, v67
	v_permlane32_swap_b32_e32 v63, v64
	v_permlane32_swap_b32_e32 v62, v66
	v_permlane32_swap_b32_e32 v61, v60
	v_permlane32_swap_b32_e32 v67, v65
	s_and_saveexec_b64 s[12:13], s[8:9]
	s_cbranch_execz .LBB0_514
	v_fmac_f32_e32 v65, 0, v66
	v_fmac_f32_e32 v60, v65, v64
	v_mul_f32_e32 v65, v60, v62
	v_pk_mul_f32 v[92:93], v[64:65], v[66:67]
	v_pk_add_f32 v[64:65], v[64:65], v[66:67]
	v_mov_b32_e32 v66, v63
	v_mov_b32_e32 v64, v92
	v_mov_b32_e32 v60, v63
	v_pk_mul_f32 v[92:93], v[92:93], v[62:63]
	v_pk_fma_f32 v[60:61], v[64:65], v[62:63], v[60:61]
	v_pk_mul_f32 v[66:67], v[92:93], v[66:67]
	s_nop 0
	v_mov_b32_e32 v67, v61
	ds_write_b64 v141, v[66:67] offset:53248
; template <bool PASS_C>
; DEVI void lru_item(const P& p, int item, int next_item, uint4& u0, uint4& u1, uint4& u2, float& cpre, char* smem) {
;     ...
; #pragma unroll
;     for (int nn = 0; nn < 4; ++nn) {
;         const int ch = 16 * nn + fr;
;         float uc[4];
; #pragma unroll
;         for (int j = 0; j < 4; ++j) {
;             const int tl = 16 * w + 4 * fq + j;
;             uc[j] = bf2f(*(const bf16_t*)(ucb + tl * 128 + ((((ch >> 3)) ^ (tl & 7)) << 4) + (ch & 7) * 2));
;         }
; #pragma unroll
;         for (int d = 0; d < 2; ++d) {
;             const float ba = prm[(5 + d) * 64 + ch], bx = prm[(7 + d) * 64 + ch], nsp8 = prm[(9 + d) * 64 + ch];
; #pragma unroll
;             for (int j = 0; j < 4; ++j) {
;                 const float r = __builtin_amdgcn_rcpf(1.0f + __builtin_amdgcn_exp2f(__builtin_fmaf(acc[(2 * d) * 4 + nn][j], -LOG2E, ba)));
;                 const float ig = __builtin_amdgcn_rcpf(1.0f + __builtin_amdgcn_exp2f(__builtin_fmaf(acc[(2 * d + 1) * 4 + nn][j], -LOG2E, bx)));
;                 const float a_ = __builtin_amdgcn_exp2f(nsp8 * r);
;                 av[nn][d][j] = a_;
;                 bv[nn][d][j] = __builtin_amdgcn_sqrtf(__builtin_fmaf(-a_, a_, 1.0f)) * ig * uc[j];
;             }
;             float A = 1.f, Bq = 0.f;
;             if (d == 0) {
; #pragma unroll
;                 for (int j = 0; j < 4; ++j) { Bq = av[nn][d][j] * Bq + bv[nn][d][j]; A *= av[nn][d][j]; }
;             } else {
; #pragma unroll
;                 for (int j = 3; j >= 0; --j) { Bq = av[nn][d][j] * Bq + bv[nn][d][j]; A *= av[nn][d][j]; }
;             }
;             float Ag[4], Bg[4];
;             rowgather4(A, Ag); rowgather4(Bq, Bg);
;             float AW = 1.f, BW = 0.f, AP = 1.f, BP = 0.f;
;             if (d == 0) {
; #pragma unroll
;                 for (int g = 0; g < 4; ++g) {
;                     if (g == fq) { AP = AW; BP = BW; }
;                     BW = Ag[g] * BW + Bg[g]; AW *= Ag[g];
;                 }
;             } else {
; #pragma unroll
;                 for (int g = 3; g >= 0; --g) {
;                     if (g == fq) { AP = AW; BP = BW; }
;                     BW = Ag[g] * BW + Bg[g]; AW *= Ag[g];
;                 }
;             }
;             apre[nn][d] = AP; bpre[nn][d] = BP;
;             if (fq == 0) { wagg[((w * 2 + d) * 64 + ch) * 2 + 0] = AW; wagg[((w * 2 + d) * 64 + ch) * 2 + 1] = BW; }
;         }
.LBB0_514:
	s_or_b64 exec, exec, s[12:13]
	v_lshlrev_b32_e32 v60, 16, v251
	v_lshlrev_b32_e32 v61, 16, v252
	v_lshlrev_b32_e32 v62, 16, v253
	v_fmamk_f32 v56, v56, 0xbfb8aa3b, v234
	v_exp_f32_e32 v56, v56
	v_fmamk_f32 v57, v57, 0xbfb8aa3b, v234
	v_fmamk_f32 v58, v58, 0xbfb8aa3b, v234
	v_fmamk_f32 v59, v59, 0xbfb8aa3b, v234
	v_add_f32_e32 v56, 1.0, v56
	v_rcp_f32_e32 v56, v56
	v_exp_f32_e32 v57, v57
	v_exp_f32_e32 v58, v58
	v_exp_f32_e32 v59, v59
	v_fmamk_f32 v52, v52, 0xbfb8aa3b, v235
	v_mul_f32_e32 v56, v255, v56
	v_add_f32_e32 v57, 1.0, v57
	v_add_f32_e32 v58, 1.0, v58
	v_add_f32_e32 v59, 1.0, v59
	v_exp_f32_e32 v52, v52
	v_rcp_f32_e32 v57, v57
	v_exp_f32_e32 v56, v56
	v_rcp_f32_e32 v58, v58
	v_rcp_f32_e32 v59, v59
	v_add_f32_e32 v52, 1.0, v52
	v_mul_f32_e32 v57, v255, v57
	v_mul_f32_e32 v58, v255, v58
	v_mul_f32_e32 v59, v255, v59
	v_rcp_f32_e32 v65, v52
	v_fma_f32 v52, -v56, v56, 1.0
	v_sqrt_f32_e32 v75, v52
	v_fmamk_f32 v53, v53, 0xbfb8aa3b, v235
	v_exp_f32_e32 v57, v57
	v_exp_f32_e32 v53, v53
	v_mul_f32_e32 v65, v65, v75
	v_mul_f32_e32 v65, v65, v60
	v_mul_f32_e32 v66, v56, v57
	v_fmac_f32_e32 v65, 0, v56
	v_add_f32_e32 v53, 1.0, v53
	v_fma_f32 v56, -v57, v57, 1.0
	v_fmamk_f32 v54, v54, 0xbfb8aa3b, v235
	v_exp_f32_e32 v58, v58
	v_rcp_f32_e32 v53, v53
	v_sqrt_f32_e32 v56, v56
	v_exp_f32_e32 v54, v54
	v_fmamk_f32 v67, v55, 0xbfb8aa3b, v235
	v_exp_f32_e32 v59, v59
	v_exp_f32_e32 v55, v67
	v_mul_f32_e32 v57, v57, v65
	v_mul_f32_e32 v53, v53, v56
	v_add_f32_e32 v54, 1.0, v54
	v_fma_f32 v56, -v58, v58, 1.0
	v_fmac_f32_e32 v57, v53, v61
	v_rcp_f32_e32 v54, v54
	v_sqrt_f32_e32 v56, v56
	v_mul_f32_e32 v53, v58, v57
	v_add_f32_e32 v55, 1.0, v55
	v_fma_f32 v57, -v59, v59, 1.0
	v_rcp_f32_e32 v55, v55
	v_sqrt_f32_e32 v57, v57
	v_mul_f32_e32 v54, v54, v56
	v_fmac_f32_e32 v53, v54, v62
	v_lshlrev_b32_e32 v63, 16, v254
	v_mul_f32_e32 v66, v58, v66
	v_mul_f32_e32 v53, v59, v53
	v_mul_f32_e32 v54, v55, v57
	v_mul_f32_e32 v52, v59, v66
	v_fmac_f32_e32 v53, v54, v63
	v_mov_b32_e32 v56, v52
	v_mov_b32_e32 v58, v53
	s_nop 0
	v_permlane16_swap_b32_e32 v52, v56
	v_permlane16_swap_b32_e32 v53, v58
	v_mov_b32_e32 v54, v52
	v_mov_b32_e32 v55, v56
	v_mov_b32_e32 v57, v53
	v_mov_b32_e32 v59, v58
	v_permlane32_swap_b32_e32 v52, v54
	v_permlane32_swap_b32_e32 v56, v55
	v_permlane32_swap_b32_e32 v53, v57
	v_permlane32_swap_b32_e32 v58, v59
	s_and_saveexec_b64 s[12:13], s[8:9]
	s_cbranch_execz .LBB0_516
	v_fmac_f32_e32 v53, 0, v52
	v_fmac_f32_e32 v58, v53, v56
	v_mul_f32_e32 v53, v58, v54
	v_pk_mul_f32 v[66:67], v[52:53], v[56:57]
	v_pk_add_f32 v[52:53], v[52:53], v[56:57]
	v_mov_b32_e32 v56, v55
	v_mov_b32_e32 v52, v66
	v_mov_b32_e32 v58, v55
	v_pk_mul_f32 v[66:67], v[66:67], v[54:55]
	v_pk_fma_f32 v[52:53], v[52:53], v[54:55], v[58:59]
	v_pk_mul_f32 v[56:57], v[66:67], v[56:57]
	s_nop 0
	v_mov_b32_e32 v57, v53
	ds_write_b64 v142, v[56:57] offset:52736
.LBB0_516:
	s_or_b64 exec, exec, s[12:13]
	v_fmamk_f32 v51, v51, 0xbfb8aa3b, v236
	v_exp_f32_e32 v51, v51
	v_fmamk_f32 v50, v50, 0xbfb8aa3b, v236
	v_exp_f32_e32 v50, v50
	v_fmamk_f32 v49, v49, 0xbfb8aa3b, v236
	v_exp_f32_e32 v49, v49
	v_add_f32_e32 v51, 1.0, v51
	v_fmamk_f32 v48, v48, 0xbfb8aa3b, v236
	v_rcp_f32_e32 v51, v51
	v_exp_f32_e32 v48, v48
	v_add_f32_e32 v50, 1.0, v50
	v_rcp_f32_e32 v50, v50
	v_add_f32_e32 v49, 1.0, v49
	v_fmamk_f32 v47, v47, 0xbfb8aa3b, v237
	v_mul_f32_e32 v51, v218, v51
	v_rcp_f32_e32 v49, v49
	v_add_f32_e32 v48, 1.0, v48
	v_exp_f32_e32 v47, v47
	v_exp_f32_e32 v51, v51
	v_rcp_f32_e32 v48, v48
	v_mul_f32_e32 v50, v218, v50
	v_exp_f32_e32 v50, v50
	v_mul_f32_e32 v49, v218, v49
	v_add_f32_e32 v47, 1.0, v47
	v_exp_f32_e32 v49, v49
	v_mul_f32_e32 v48, v218, v48
	v_rcp_f32_e32 v54, v47
	v_fma_f32 v47, -v51, v51, 1.0
	v_exp_f32_e32 v48, v48
	v_sqrt_f32_e32 v55, v47
	v_fmamk_f32 v46, v46, 0xbfb8aa3b, v237
	v_mul_f32_e32 v52, v51, v50
	v_exp_f32_e32 v46, v46
	v_mul_f32_e32 v52, v49, v52
	v_mul_f32_e32 v47, v48, v52
	v_mul_f32_e32 v52, v54, v55
	v_mul_f32_e32 v52, v52, v63
	v_fmac_f32_e32 v52, 0, v51
	v_add_f32_e32 v46, 1.0, v46
	v_fma_f32 v51, -v50, v50, 1.0
	v_rcp_f32_e32 v46, v46
	v_sqrt_f32_e32 v51, v51
	v_fmamk_f32 v45, v45, 0xbfb8aa3b, v237
	v_exp_f32_e32 v45, v45
	v_fmamk_f32 v53, v44, 0xbfb8aa3b, v237
	v_mul_f32_e32 v50, v50, v52
	v_mul_f32_e32 v46, v46, v51
	v_exp_f32_e32 v44, v53
	v_fmac_f32_e32 v50, v46, v62
	v_mul_f32_e32 v46, v49, v50
	v_add_f32_e32 v45, 1.0, v45
	v_fma_f32 v49, -v49, v49, 1.0
	v_rcp_f32_e32 v45, v45
	v_sqrt_f32_e32 v49, v49
	v_add_f32_e32 v44, 1.0, v44
	v_fma_f32 v50, -v48, v48, 1.0
	v_rcp_f32_e32 v44, v44
	v_sqrt_f32_e32 v50, v50
	v_mul_f32_e32 v45, v45, v49
	v_fmac_f32_e32 v46, v45, v61
	v_mul_f32_e32 v45, v48, v46
	v_mul_f32_e32 v44, v44, v50
	v_fmac_f32_e32 v45, v44, v60
	v_mov_b32_e32 v46, v47
	v_mov_b32_e32 v51, v45
	s_nop 0
	v_permlane16_swap_b32_e32 v47, v46
	v_permlane16_swap_b32_e32 v45, v51
	v_mov_b32_e32 v48, v47
	v_mov_b32_e32 v50, v46
	v_mov_b32_e32 v44, v45
	v_mov_b32_e32 v49, v51
	v_permlane32_swap_b32_e32 v47, v48
	v_permlane32_swap_b32_e32 v46, v50
	v_permlane32_swap_b32_e32 v45, v44
	v_permlane32_swap_b32_e32 v51, v49
	s_and_saveexec_b64 s[12:13], s[8:9]
	s_cbranch_execz .LBB0_518
	v_fmac_f32_e32 v49, 0, v50
	v_fmac_f32_e32 v44, v49, v48
	v_mul_f32_e32 v49, v44, v46
	v_pk_mul_f32 v[52:53], v[48:49], v[50:51]
	v_pk_add_f32 v[48:49], v[48:49], v[50:51]
	v_mov_b32_e32 v50, v47
	v_mov_b32_e32 v48, v52
	v_mov_b32_e32 v44, v47
	v_pk_mul_f32 v[52:53], v[52:53], v[46:47]
	v_pk_fma_f32 v[44:45], v[48:49], v[46:47], v[44:45]
	v_pk_mul_f32 v[50:51], v[52:53], v[50:51]
	s_nop 0
	v_mov_b32_e32 v51, v45
	ds_write_b64 v142, v[50:51] offset:53248
; template <bool PASS_C>
; DEVI void lru_item(const P& p, int item, int next_item, uint4& u0, uint4& u1, uint4& u2, float& cpre, char* smem) {
;     ...
; #pragma unroll
;     for (int nn = 0; nn < 4; ++nn) {
;         const int ch = 16 * nn + fr;
;         float uc[4];
; #pragma unroll
;         for (int j = 0; j < 4; ++j) {
;             const int tl = 16 * w + 4 * fq + j;
;             uc[j] = bf2f(*(const bf16_t*)(ucb + tl * 128 + ((((ch >> 3)) ^ (tl & 7)) << 4) + (ch & 7) * 2));
;         }
; #pragma unroll
;         for (int d = 0; d < 2; ++d) {
;             const float ba = prm[(5 + d) * 64 + ch], bx = prm[(7 + d) * 64 + ch], nsp8 = prm[(9 + d) * 64 + ch];
; #pragma unroll
;             for (int j = 0; j < 4; ++j) {
;                 const float r = __builtin_amdgcn_rcpf(1.0f + __builtin_amdgcn_exp2f(__builtin_fmaf(acc[(2 * d) * 4 + nn][j], -LOG2E, ba)));
;                 const float ig = __builtin_amdgcn_rcpf(1.0f + __builtin_amdgcn_exp2f(__builtin_fmaf(acc[(2 * d + 1) * 4 + nn][j], -LOG2E, bx)));
;                 const float a_ = __builtin_amdgcn_exp2f(nsp8 * r);
;                 av[nn][d][j] = a_;
;                 bv[nn][d][j] = __builtin_amdgcn_sqrtf(__builtin_fmaf(-a_, a_, 1.0f)) * ig * uc[j];
;             }
;             float A = 1.f, Bq = 0.f;
;             if (d == 0) {
; #pragma unroll
;                 for (int j = 0; j < 4; ++j) { Bq = av[nn][d][j] * Bq + bv[nn][d][j]; A *= av[nn][d][j]; }
;             } else {
; #pragma unroll
;                 for (int j = 3; j >= 0; --j) { Bq = av[nn][d][j] * Bq + bv[nn][d][j]; A *= av[nn][d][j]; }
;             }
;             float Ag[4], Bg[4];
;             rowgather4(A, Ag); rowgather4(Bq, Bg);
;             float AW = 1.f, BW = 0.f, AP = 1.f, BP = 0.f;
;             if (d == 0) {
; #pragma unroll
;                 for (int g = 0; g < 4; ++g) {
;                     if (g == fq) { AP = AW; BP = BW; }
;                     BW = Ag[g] * BW + Bg[g]; AW *= Ag[g];
;                 }
;             } else {
; #pragma unroll
;                 for (int g = 3; g >= 0; --g) {
;                     if (g == fq) { AP = AW; BP = BW; }
;                     BW = Ag[g] * BW + Bg[g]; AW *= Ag[g];
;                 }
;             }
;             apre[nn][d] = AP; bpre[nn][d] = BP;
;             if (fq == 0) { wagg[((w * 2 + d) * 64 + ch) * 2 + 0] = AW; wagg[((w * 2 + d) * 64 + ch) * 2 + 1] = BW; }
;         }
.LBB0_518:
	s_or_b64 exec, exec, s[12:13]
	v_lshlrev_b32_e32 v44, 16, v219
	v_lshlrev_b32_e32 v45, 16, v220
	v_lshlrev_b32_e32 v46, 16, v221
	v_fmamk_f32 v40, v40, 0xbfb8aa3b, v238
	v_exp_f32_e32 v40, v40
	v_fmamk_f32 v41, v41, 0xbfb8aa3b, v238
	v_fmamk_f32 v42, v42, 0xbfb8aa3b, v238
	v_fmamk_f32 v43, v43, 0xbfb8aa3b, v238
	v_add_f32_e32 v40, 1.0, v40
	v_rcp_f32_e32 v40, v40
	v_exp_f32_e32 v41, v41
	v_exp_f32_e32 v42, v42
	v_exp_f32_e32 v43, v43
	v_fmamk_f32 v36, v36, 0xbfb8aa3b, v239
	v_mul_f32_e32 v40, v223, v40
	v_add_f32_e32 v41, 1.0, v41
	v_add_f32_e32 v42, 1.0, v42
	v_add_f32_e32 v43, 1.0, v43
	v_exp_f32_e32 v36, v36
	v_rcp_f32_e32 v41, v41
	v_exp_f32_e32 v40, v40
	v_rcp_f32_e32 v42, v42
	v_rcp_f32_e32 v43, v43
	v_add_f32_e32 v36, 1.0, v36
	v_mul_f32_e32 v41, v223, v41
	v_mul_f32_e32 v42, v223, v42
	v_mul_f32_e32 v43, v223, v43
	v_rcp_f32_e32 v49, v36
	v_fma_f32 v36, -v40, v40, 1.0
	v_sqrt_f32_e32 v52, v36
	v_fmamk_f32 v37, v37, 0xbfb8aa3b, v239
	v_exp_f32_e32 v41, v41
	v_exp_f32_e32 v37, v37
	v_mul_f32_e32 v49, v49, v52
	v_mul_f32_e32 v49, v49, v44
	v_mul_f32_e32 v50, v40, v41
	v_fmac_f32_e32 v49, 0, v40
	v_add_f32_e32 v37, 1.0, v37
	v_fma_f32 v40, -v41, v41, 1.0
	v_fmamk_f32 v38, v38, 0xbfb8aa3b, v239
	v_exp_f32_e32 v42, v42
	v_rcp_f32_e32 v37, v37
	v_sqrt_f32_e32 v40, v40
	v_exp_f32_e32 v38, v38
	v_fmamk_f32 v51, v39, 0xbfb8aa3b, v239
	v_exp_f32_e32 v43, v43
	v_exp_f32_e32 v39, v51
	v_mul_f32_e32 v41, v41, v49
	v_mul_f32_e32 v37, v37, v40
	v_add_f32_e32 v38, 1.0, v38
	v_fma_f32 v40, -v42, v42, 1.0
	v_fmac_f32_e32 v41, v37, v45
	v_rcp_f32_e32 v38, v38
	v_sqrt_f32_e32 v40, v40
	v_mul_f32_e32 v37, v42, v41
	v_add_f32_e32 v39, 1.0, v39
	v_fma_f32 v41, -v43, v43, 1.0
	v_rcp_f32_e32 v39, v39
	v_sqrt_f32_e32 v41, v41
	v_mul_f32_e32 v38, v38, v40
	v_fmac_f32_e32 v37, v38, v46
	v_lshlrev_b32_e32 v47, 16, v222
	v_mul_f32_e32 v50, v42, v50
	v_mul_f32_e32 v37, v43, v37
	v_mul_f32_e32 v38, v39, v41
	v_mul_f32_e32 v36, v43, v50
	v_fmac_f32_e32 v37, v38, v47
	v_mov_b32_e32 v40, v36
	v_mov_b32_e32 v42, v37
	s_nop 0
	v_permlane16_swap_b32_e32 v36, v40
	v_permlane16_swap_b32_e32 v37, v42
	v_mov_b32_e32 v38, v36
	v_mov_b32_e32 v39, v40
	v_mov_b32_e32 v41, v37
	v_mov_b32_e32 v43, v42
	v_permlane32_swap_b32_e32 v36, v38
	v_permlane32_swap_b32_e32 v40, v39
	v_permlane32_swap_b32_e32 v37, v41
	v_permlane32_swap_b32_e32 v42, v43
	s_and_saveexec_b64 s[12:13], s[8:9]
	s_cbranch_execz .LBB0_520
	v_fmac_f32_e32 v37, 0, v36
	v_fmac_f32_e32 v42, v37, v40
	v_mul_f32_e32 v37, v42, v38
	v_pk_mul_f32 v[50:51], v[36:37], v[40:41]
	v_pk_add_f32 v[36:37], v[36:37], v[40:41]
	v_mov_b32_e32 v40, v39
	v_mov_b32_e32 v36, v50
	v_mov_b32_e32 v42, v39
	v_pk_mul_f32 v[50:51], v[50:51], v[38:39]
	v_pk_fma_f32 v[36:37], v[36:37], v[38:39], v[42:43]
	v_pk_mul_f32 v[40:41], v[50:51], v[40:41]
	s_nop 0
	v_mov_b32_e32 v41, v37
	ds_write_b64 v143, v[40:41] offset:52736
.LBB0_520:
	s_or_b64 exec, exec, s[12:13]
	v_fmamk_f32 v35, v35, 0xbfb8aa3b, v240
	v_exp_f32_e32 v35, v35
	v_fmamk_f32 v34, v34, 0xbfb8aa3b, v240
	v_exp_f32_e32 v34, v34
	v_fmamk_f32 v33, v33, 0xbfb8aa3b, v240
	v_exp_f32_e32 v33, v33
	v_add_f32_e32 v35, 1.0, v35
	v_fmamk_f32 v32, v32, 0xbfb8aa3b, v240
	v_rcp_f32_e32 v35, v35
	v_exp_f32_e32 v32, v32
	v_add_f32_e32 v34, 1.0, v34
	v_rcp_f32_e32 v34, v34
	v_add_f32_e32 v33, 1.0, v33
	v_fmamk_f32 v31, v31, 0xbfb8aa3b, v241
	v_mul_f32_e32 v35, v224, v35
	v_rcp_f32_e32 v33, v33
	v_add_f32_e32 v32, 1.0, v32
	v_exp_f32_e32 v31, v31
	v_exp_f32_e32 v35, v35
	v_rcp_f32_e32 v32, v32
	v_mul_f32_e32 v34, v224, v34
	v_exp_f32_e32 v34, v34
	v_mul_f32_e32 v33, v224, v33
	v_add_f32_e32 v31, 1.0, v31
	v_exp_f32_e32 v33, v33
	v_mul_f32_e32 v32, v224, v32
	v_rcp_f32_e32 v38, v31
	v_fma_f32 v31, -v35, v35, 1.0
	v_exp_f32_e32 v32, v32
	v_sqrt_f32_e32 v39, v31
	v_fmamk_f32 v30, v30, 0xbfb8aa3b, v241
	v_mul_f32_e32 v36, v35, v34
	v_exp_f32_e32 v30, v30
	v_mul_f32_e32 v36, v33, v36
	v_mul_f32_e32 v31, v32, v36
	v_mul_f32_e32 v36, v38, v39
	v_mul_f32_e32 v36, v36, v47
	v_fmac_f32_e32 v36, 0, v35
	v_add_f32_e32 v30, 1.0, v30
	v_fma_f32 v35, -v34, v34, 1.0
	v_rcp_f32_e32 v30, v30
	v_sqrt_f32_e32 v35, v35
	v_fmamk_f32 v29, v29, 0xbfb8aa3b, v241
	v_exp_f32_e32 v29, v29
	v_fmamk_f32 v37, v28, 0xbfb8aa3b, v241
	v_mul_f32_e32 v34, v34, v36
	v_mul_f32_e32 v30, v30, v35
	v_exp_f32_e32 v28, v37
	v_fmac_f32_e32 v34, v30, v46
	v_mul_f32_e32 v30, v33, v34
	v_add_f32_e32 v29, 1.0, v29
	v_fma_f32 v33, -v33, v33, 1.0
	v_rcp_f32_e32 v29, v29
	v_sqrt_f32_e32 v33, v33
	v_add_f32_e32 v28, 1.0, v28
	v_fma_f32 v34, -v32, v32, 1.0
	v_rcp_f32_e32 v28, v28
	v_sqrt_f32_e32 v34, v34
	v_mul_f32_e32 v29, v29, v33
	v_fmac_f32_e32 v30, v29, v45
	v_mul_f32_e32 v29, v32, v30
	v_mul_f32_e32 v28, v28, v34
	v_fmac_f32_e32 v29, v28, v44
	v_mov_b32_e32 v30, v31
	v_mov_b32_e32 v35, v29
	s_nop 0
	v_permlane16_swap_b32_e32 v31, v30
	v_permlane16_swap_b32_e32 v29, v35
	v_mov_b32_e32 v32, v31
	v_mov_b32_e32 v34, v30
	v_mov_b32_e32 v28, v29
	v_mov_b32_e32 v33, v35
	v_permlane32_swap_b32_e32 v31, v32
	v_permlane32_swap_b32_e32 v30, v34
	v_permlane32_swap_b32_e32 v29, v28
	v_permlane32_swap_b32_e32 v35, v33
	s_and_saveexec_b64 s[12:13], s[8:9]
	s_cbranch_execz .LBB0_522
	v_fmac_f32_e32 v33, 0, v34
	v_fmac_f32_e32 v28, v33, v32
	v_mul_f32_e32 v33, v28, v30
	v_pk_mul_f32 v[36:37], v[32:33], v[34:35]
	v_pk_add_f32 v[32:33], v[32:33], v[34:35]
	v_mov_b32_e32 v34, v31
	v_mov_b32_e32 v32, v36
	v_mov_b32_e32 v28, v31
	v_pk_mul_f32 v[36:37], v[36:37], v[30:31]
	v_pk_fma_f32 v[28:29], v[32:33], v[30:31], v[28:29]
	v_pk_mul_f32 v[34:35], v[36:37], v[34:35]
	s_nop 0
	v_mov_b32_e32 v35, v29
	ds_write_b64 v143, v[34:35] offset:53248
; template <bool PASS_C>
; DEVI void lru_item(const P& p, int item, int next_item, uint4& u0, uint4& u1, uint4& u2, float& cpre, char* smem) {
;     ...
; #pragma unroll
;     for (int nn = 0; nn < 4; ++nn) {
;         const int ch = 16 * nn + fr;
;         float uc[4];
; #pragma unroll
;         for (int j = 0; j < 4; ++j) {
;             const int tl = 16 * w + 4 * fq + j;
;             uc[j] = bf2f(*(const bf16_t*)(ucb + tl * 128 + ((((ch >> 3)) ^ (tl & 7)) << 4) + (ch & 7) * 2));
;         }
; #pragma unroll
;         for (int d = 0; d < 2; ++d) {
;             const float ba = prm[(5 + d) * 64 + ch], bx = prm[(7 + d) * 64 + ch], nsp8 = prm[(9 + d) * 64 + ch];
; #pragma unroll
;             for (int j = 0; j < 4; ++j) {
;                 const float r = __builtin_amdgcn_rcpf(1.0f + __builtin_amdgcn_exp2f(__builtin_fmaf(acc[(2 * d) * 4 + nn][j], -LOG2E, ba)));
;                 const float ig = __builtin_amdgcn_rcpf(1.0f + __builtin_amdgcn_exp2f(__builtin_fmaf(acc[(2 * d + 1) * 4 + nn][j], -LOG2E, bx)));
;                 const float a_ = __builtin_amdgcn_exp2f(nsp8 * r);
;                 av[nn][d][j] = a_;
;                 bv[nn][d][j] = __builtin_amdgcn_sqrtf(__builtin_fmaf(-a_, a_, 1.0f)) * ig * uc[j];
;             }
;             float A = 1.f, Bq = 0.f;
;             if (d == 0) {
; #pragma unroll
;                 for (int j = 0; j < 4; ++j) { Bq = av[nn][d][j] * Bq + bv[nn][d][j]; A *= av[nn][d][j]; }
;             } else {
; #pragma unroll
;                 for (int j = 3; j >= 0; --j) { Bq = av[nn][d][j] * Bq + bv[nn][d][j]; A *= av[nn][d][j]; }
;             }
;             float Ag[4], Bg[4];
;             rowgather4(A, Ag); rowgather4(Bq, Bg);
;             float AW = 1.f, BW = 0.f, AP = 1.f, BP = 0.f;
;             if (d == 0) {
; #pragma unroll
;                 for (int g = 0; g < 4; ++g) {
;                     if (g == fq) { AP = AW; BP = BW; }
;                     BW = Ag[g] * BW + Bg[g]; AW *= Ag[g];
;                 }
;             } else {
; #pragma unroll
;                 for (int g = 3; g >= 0; --g) {
;                     if (g == fq) { AP = AW; BP = BW; }
;                     BW = Ag[g] * BW + Bg[g]; AW *= Ag[g];
;                 }
;             }
;             apre[nn][d] = AP; bpre[nn][d] = BP;
;             if (fq == 0) { wagg[((w * 2 + d) * 64 + ch) * 2 + 0] = AW; wagg[((w * 2 + d) * 64 + ch) * 2 + 1] = BW; }
;         }
.LBB0_522:
	s_or_b64 exec, exec, s[12:13]
	v_lshlrev_b32_e32 v28, 16, v225
	v_lshlrev_b32_e32 v29, 16, v226
	v_lshlrev_b32_e32 v30, 16, v227
	v_fmamk_f32 v24, v24, 0xbfb8aa3b, v242
	v_exp_f32_e32 v24, v24
	v_fmamk_f32 v25, v25, 0xbfb8aa3b, v242
	v_fmamk_f32 v26, v26, 0xbfb8aa3b, v242
	v_fmamk_f32 v27, v27, 0xbfb8aa3b, v242
	v_add_f32_e32 v24, 1.0, v24
	v_rcp_f32_e32 v24, v24
	v_exp_f32_e32 v25, v25
	v_exp_f32_e32 v26, v26
	v_exp_f32_e32 v27, v27
	v_fmamk_f32 v20, v20, 0xbfb8aa3b, v243
	v_mul_f32_e32 v24, v229, v24
	v_add_f32_e32 v25, 1.0, v25
	v_add_f32_e32 v26, 1.0, v26
	v_add_f32_e32 v27, 1.0, v27
	v_exp_f32_e32 v20, v20
	v_rcp_f32_e32 v25, v25
	v_exp_f32_e32 v24, v24
	v_rcp_f32_e32 v26, v26
	v_rcp_f32_e32 v27, v27
	v_add_f32_e32 v20, 1.0, v20
	v_mul_f32_e32 v25, v229, v25
	v_mul_f32_e32 v26, v229, v26
	v_mul_f32_e32 v27, v229, v27
	v_rcp_f32_e32 v33, v20
	v_fma_f32 v20, -v24, v24, 1.0
	v_sqrt_f32_e32 v36, v20
	v_fmamk_f32 v21, v21, 0xbfb8aa3b, v243
	v_exp_f32_e32 v25, v25
	v_exp_f32_e32 v21, v21
	v_mul_f32_e32 v33, v33, v36
	v_mul_f32_e32 v33, v33, v28
	v_mul_f32_e32 v34, v24, v25
	v_fmac_f32_e32 v33, 0, v24
	v_add_f32_e32 v21, 1.0, v21
	v_fma_f32 v24, -v25, v25, 1.0
	v_fmamk_f32 v22, v22, 0xbfb8aa3b, v243
	v_exp_f32_e32 v26, v26
	v_rcp_f32_e32 v21, v21
	v_sqrt_f32_e32 v24, v24
	v_exp_f32_e32 v22, v22
	v_fmamk_f32 v35, v23, 0xbfb8aa3b, v243
	v_exp_f32_e32 v27, v27
	v_exp_f32_e32 v23, v35
	v_mul_f32_e32 v25, v25, v33
	v_mul_f32_e32 v21, v21, v24
	v_add_f32_e32 v22, 1.0, v22
	v_fma_f32 v24, -v26, v26, 1.0
	v_fmac_f32_e32 v25, v21, v29
	v_rcp_f32_e32 v22, v22
	v_sqrt_f32_e32 v24, v24
	v_mul_f32_e32 v21, v26, v25
	v_add_f32_e32 v23, 1.0, v23
	v_fma_f32 v25, -v27, v27, 1.0
	v_rcp_f32_e32 v23, v23
	v_sqrt_f32_e32 v25, v25
	v_mul_f32_e32 v22, v22, v24
	v_fmac_f32_e32 v21, v22, v30
	v_lshlrev_b32_e32 v31, 16, v228
	v_mul_f32_e32 v34, v26, v34
	v_mul_f32_e32 v21, v27, v21
	v_mul_f32_e32 v22, v23, v25
	v_mul_f32_e32 v20, v27, v34
	v_fmac_f32_e32 v21, v22, v31
	v_mov_b32_e32 v24, v20
	v_mov_b32_e32 v26, v21
	s_nop 0
	v_permlane16_swap_b32_e32 v20, v24
	v_permlane16_swap_b32_e32 v21, v26
	v_mov_b32_e32 v22, v20
	v_mov_b32_e32 v23, v24
	v_mov_b32_e32 v25, v21
	v_mov_b32_e32 v27, v26
	v_permlane32_swap_b32_e32 v20, v22
	v_permlane32_swap_b32_e32 v24, v23
	v_permlane32_swap_b32_e32 v21, v25
	v_permlane32_swap_b32_e32 v26, v27
	s_and_saveexec_b64 s[12:13], s[8:9]
	s_cbranch_execz .LBB0_524
	v_fmac_f32_e32 v21, 0, v20
	v_fmac_f32_e32 v26, v21, v24
	v_mul_f32_e32 v21, v26, v22
	v_pk_mul_f32 v[34:35], v[20:21], v[24:25]
	v_pk_add_f32 v[20:21], v[20:21], v[24:25]
	v_mov_b32_e32 v24, v23
	v_mov_b32_e32 v20, v34
	v_mov_b32_e32 v26, v23
	v_pk_mul_f32 v[34:35], v[34:35], v[22:23]
	v_pk_fma_f32 v[20:21], v[20:21], v[22:23], v[26:27]
	v_pk_mul_f32 v[24:25], v[34:35], v[24:25]
	s_nop 0
	v_mov_b32_e32 v25, v21
	ds_write_b64 v144, v[24:25] offset:52736
.LBB0_524:
	s_or_b64 exec, exec, s[12:13]
	v_fmamk_f32 v19, v19, 0xbfb8aa3b, v244
	v_exp_f32_e32 v19, v19
	v_fmamk_f32 v18, v18, 0xbfb8aa3b, v244
	v_exp_f32_e32 v18, v18
	v_fmamk_f32 v17, v17, 0xbfb8aa3b, v244
	v_exp_f32_e32 v17, v17
	v_add_f32_e32 v19, 1.0, v19
	v_fmamk_f32 v16, v16, 0xbfb8aa3b, v244
	v_rcp_f32_e32 v19, v19
	v_exp_f32_e32 v16, v16
	v_add_f32_e32 v18, 1.0, v18
	v_rcp_f32_e32 v18, v18
	v_add_f32_e32 v17, 1.0, v17
	v_fmamk_f32 v15, v15, 0xbfb8aa3b, v245
	v_mul_f32_e32 v19, v231, v19
	v_rcp_f32_e32 v17, v17
	v_add_f32_e32 v16, 1.0, v16
	v_exp_f32_e32 v15, v15
	v_exp_f32_e32 v19, v19
	v_rcp_f32_e32 v16, v16
	v_mul_f32_e32 v18, v231, v18
	v_exp_f32_e32 v18, v18
	v_mul_f32_e32 v17, v231, v17
	v_add_f32_e32 v15, 1.0, v15
	v_exp_f32_e32 v17, v17
	v_mul_f32_e32 v16, v231, v16
	v_rcp_f32_e32 v22, v15
	v_fma_f32 v15, -v19, v19, 1.0
	v_exp_f32_e32 v16, v16
	v_sqrt_f32_e32 v23, v15
	v_fmamk_f32 v14, v14, 0xbfb8aa3b, v245
	v_mul_f32_e32 v20, v19, v18
	v_exp_f32_e32 v14, v14
	v_mul_f32_e32 v20, v17, v20
	v_mul_f32_e32 v15, v16, v20
	v_mul_f32_e32 v20, v22, v23
	v_mul_f32_e32 v20, v20, v31
	v_fmac_f32_e32 v20, 0, v19
	v_add_f32_e32 v14, 1.0, v14
	v_fma_f32 v19, -v18, v18, 1.0
	v_rcp_f32_e32 v14, v14
	v_sqrt_f32_e32 v19, v19
	v_fmamk_f32 v13, v13, 0xbfb8aa3b, v245
	v_exp_f32_e32 v13, v13
	v_fmamk_f32 v21, v12, 0xbfb8aa3b, v245
	v_mul_f32_e32 v18, v18, v20
	v_mul_f32_e32 v14, v14, v19
	v_exp_f32_e32 v12, v21
	v_fmac_f32_e32 v18, v14, v30
	v_mul_f32_e32 v14, v17, v18
	v_add_f32_e32 v13, 1.0, v13
	v_fma_f32 v17, -v17, v17, 1.0
	v_rcp_f32_e32 v13, v13
	v_sqrt_f32_e32 v17, v17
	v_add_f32_e32 v12, 1.0, v12
	v_fma_f32 v18, -v16, v16, 1.0
	v_rcp_f32_e32 v12, v12
	v_sqrt_f32_e32 v18, v18
	v_mul_f32_e32 v13, v13, v17
	v_fmac_f32_e32 v14, v13, v29
	v_mul_f32_e32 v13, v16, v14
	v_mul_f32_e32 v12, v12, v18
	v_fmac_f32_e32 v13, v12, v28
	v_mov_b32_e32 v14, v15
	v_mov_b32_e32 v19, v13
	s_nop 0
	v_permlane16_swap_b32_e32 v15, v14
	v_permlane16_swap_b32_e32 v13, v19
	v_mov_b32_e32 v16, v15
	v_mov_b32_e32 v18, v14
	v_mov_b32_e32 v12, v13
	v_mov_b32_e32 v17, v19
	v_permlane32_swap_b32_e32 v15, v16
	v_permlane32_swap_b32_e32 v14, v18
	v_permlane32_swap_b32_e32 v13, v12
	v_permlane32_swap_b32_e32 v19, v17
	s_and_saveexec_b64 s[12:13], s[8:9]
	s_cbranch_execz .LBB0_526
	v_fmac_f32_e32 v17, 0, v18
	v_fmac_f32_e32 v12, v17, v16
	v_mul_f32_e32 v17, v12, v14
	v_pk_mul_f32 v[20:21], v[16:17], v[18:19]
	v_pk_add_f32 v[16:17], v[16:17], v[18:19]
	v_mov_b32_e32 v18, v15
	v_mov_b32_e32 v16, v20
	v_mov_b32_e32 v12, v15
	v_pk_mul_f32 v[20:21], v[20:21], v[14:15]
	v_pk_fma_f32 v[12:13], v[16:17], v[14:15], v[12:13]
	v_pk_mul_f32 v[18:19], v[20:21], v[18:19]
	s_nop 0
	v_mov_b32_e32 v19, v13
	ds_write_b64 v144, v[18:19] offset:53248

; DEVI unsigned pk2(float lo, float hi) { f32x2 v = {lo, hi}; bf16x2_t b = __builtin_convertvector(v, bf16x2_t); return __builtin_bit_cast(unsigned, b); }
; DEVI float bflo(unsigned u) { return __uint_as_float(u << 16); }
; DEVI float bfhi(unsigned u) { return __uint_as_float(u & 0xffff0000u); }
; template <bool PASS_C>
; DEVI void lru_item(const P& p, int item, int next_item, uint4& u0, uint4& u1, uint4& u2, float& cpre, char* smem) {
;     ...
;     {
;         const int tok = tid >> 2, cg0 = (tid & 3) * 16;
;         uint4 r[4][2];
; #pragma unroll
;         for (int k = 0; k < 4; ++k) { r[k][0] = *(const uint4*)(us + (tok + k) * 64 + cg0); r[k][1] = *(const uint4*)(us + (tok + k) * 64 + cg0 + 8); }
;         float val[16];
; #pragma unroll
;         for (int e = 0; e < 16; ++e) {
;             const int ch = cg0 + e;
;             float a = prm[4 * 64 + ch];
; #pragma unroll
;             for (int k = 0; k < 4; ++k) {
;                 const uint4 q = r[k][e >> 3];
;                 const unsigned wd = ((e >> 1) & 3) == 0 ? q.x : (((e >> 1) & 3) == 1 ? q.y : (((e >> 1) & 3) == 2 ? q.z : q.w));
;                 a += prm[k * 64 + ch] * ((e & 1) ? bfhi(wd) : bflo(wd));
;             }
;             val[e] = a;
;         }
;         uint4 o;
;         o.x = pk2(val[0], val[1]); o.y = pk2(val[2], val[3]); o.z = pk2(val[4], val[5]); o.w = pk2(val[6], val[7]);
;         *(uint4*)(ucb + tok * 128 + ((((cg0 >> 3) + 0) ^ (tok & 7)) << 4)) = o;
;         o.x = pk2(val[8], val[9]); o.y = pk2(val[10], val[11]); o.z = pk2(val[12], val[13]); o.w = pk2(val[14], val[15]);
;         *(uint4*)(ucb + tok * 128 + ((((cg0 >> 3) + 1) ^ (tok & 7)) << 4)) = o;
;     }
.LBB0_739:
	v_lshlrev_b64 v[106:107], 10, v[22:23]
	s_waitcnt lgkmcnt(0)
	s_barrier
	ds_read_b128 v[42:45], v127 offset:35840
	ds_read_b128 v[22:25], v127 offset:35856
	ds_read_b128 v[46:49], v127 offset:35968
	ds_read_b128 v[26:29], v127 offset:35984
	ds_read_b128 v[50:53], v127 offset:36096
	ds_read_b128 v[30:33], v127 offset:36112
	ds_read_b128 v[54:57], v127 offset:36224
	ds_read_b128 v[34:37], v127 offset:36240
	ds_read_b128 v[58:61], v117 offset:33792
	ds_read_b128 v[62:65], v117 offset:32768
	ds_read_b128 v[66:69], v117 offset:32784
	ds_read_b128 v[70:73], v117 offset:32800
	ds_read_b128 v[38:41], v117 offset:32816
	ds_read_b128 v[74:77], v117 offset:33024
	ds_read_b128 v[158:161], v117 offset:33808
	s_waitcnt lgkmcnt(14)
	v_lshlrev_b32_e32 v162, 16, v42
	v_and_b32_e32 v163, 0xffff0000, v42
	s_waitcnt lgkmcnt(5)
	v_pk_fma_f32 v[58:59], v[62:63], v[162:163], v[58:59]
	ds_read_b128 v[162:165], v117 offset:33280
	ds_read_b128 v[166:169], v117 offset:33536
	ds_read_b128 v[184:187], v117 offset:33040
	v_lshlrev_b32_e32 v42, 16, v43
	v_and_b32_e32 v43, 0xffff0000, v43
	v_lshlrev_b32_e32 v170, 16, v46
	v_and_b32_e32 v171, 0xffff0000, v46
	v_lshlrev_b32_e32 v46, 16, v47
	v_and_b32_e32 v47, 0xffff0000, v47
	v_pk_fma_f32 v[42:43], v[64:65], v[42:43], v[60:61]
	v_lshlrev_b32_e32 v192, 16, v50
	v_and_b32_e32 v193, 0xffff0000, v50
	s_waitcnt lgkmcnt(4)
	v_pk_fma_f32 v[58:59], v[74:75], v[170:171], v[58:59]
	ds_read_b128 v[188:191], v117 offset:33296
	v_lshlrev_b32_e32 v50, 16, v51
	v_and_b32_e32 v51, 0xffff0000, v51
	v_pk_fma_f32 v[42:43], v[76:77], v[46:47], v[42:43]
	v_lshlrev_b32_e32 v196, 16, v54
	v_and_b32_e32 v197, 0xffff0000, v54
	s_waitcnt lgkmcnt(3)
	v_pk_fma_f32 v[58:59], v[162:163], v[192:193], v[58:59]
	ds_read_b128 v[192:195], v117 offset:33552
	v_lshlrev_b32_e32 v54, 16, v55
	v_and_b32_e32 v55, 0xffff0000, v55
	v_pk_fma_f32 v[42:43], v[164:165], v[50:51], v[42:43]
	v_lshlrev_b32_e32 v46, 16, v48
	s_waitcnt lgkmcnt(3)
	v_pk_fma_f32 v[164:165], v[168:169], v[54:55], v[42:43]
	v_lshlrev_b32_e32 v42, 16, v44
	v_and_b32_e32 v43, 0xffff0000, v44
	v_and_b32_e32 v47, 0xffff0000, v48
	v_pk_fma_f32 v[42:43], v[66:67], v[42:43], v[158:159]
	v_lshlrev_b32_e32 v50, 16, v52
	v_and_b32_e32 v51, 0xffff0000, v52
	s_waitcnt lgkmcnt(2)
	v_pk_fma_f32 v[42:43], v[184:185], v[46:47], v[42:43]
	v_lshlrev_b32_e32 v54, 16, v56
	v_and_b32_e32 v55, 0xffff0000, v56
	s_waitcnt lgkmcnt(1)
	v_pk_fma_f32 v[42:43], v[188:189], v[50:51], v[42:43]
	v_lshlrev_b32_e32 v44, 16, v49
	s_waitcnt lgkmcnt(0)
	v_pk_fma_f32 v[158:159], v[192:193], v[54:55], v[42:43]
	v_lshlrev_b32_e32 v42, 16, v45
	v_and_b32_e32 v43, 0xffff0000, v45
	v_and_b32_e32 v45, 0xffff0000, v49
	v_pk_fma_f32 v[42:43], v[68:69], v[42:43], v[160:161]
	v_lshlrev_b32_e32 v46, 16, v53
	v_and_b32_e32 v47, 0xffff0000, v53
	v_pk_fma_f32 v[42:43], v[186:187], v[44:45], v[42:43]
	v_lshlrev_b32_e32 v48, 16, v57
	v_and_b32_e32 v49, 0xffff0000, v57
	v_pk_fma_f32 v[42:43], v[190:191], v[46:47], v[42:43]
	v_lshlrev_b32_e32 v54, 16, v22
	v_pk_fma_f32 v[160:161], v[194:195], v[48:49], v[42:43]
	ds_read_b128 v[42:45], v117 offset:33824
	ds_read_b128 v[46:49], v117 offset:33056
	ds_read_b128 v[50:53], v117 offset:33840
	v_and_b32_e32 v55, 0xffff0000, v22
	v_pk_fma_f32 v[162:163], v[166:167], v[196:197], v[58:59]
	v_lshlrev_b32_e32 v22, 16, v23
	s_waitcnt lgkmcnt(2)
	v_pk_fma_f32 v[42:43], v[70:71], v[54:55], v[42:43]
	ds_read_b128 v[54:57], v117 offset:33312
	ds_read_b128 v[58:61], v117 offset:33568
	ds_read_b128 v[62:65], v117 offset:33072
	v_and_b32_e32 v23, 0xffff0000, v23
	v_lshlrev_b32_e32 v66, 16, v26
	v_and_b32_e32 v67, 0xffff0000, v26
	v_lshlrev_b32_e32 v26, 16, v27
	v_and_b32_e32 v27, 0xffff0000, v27
	v_pk_fma_f32 v[22:23], v[72:73], v[22:23], v[44:45]
	v_lshlrev_b32_e32 v74, 16, v30
	v_and_b32_e32 v75, 0xffff0000, v30
	s_waitcnt lgkmcnt(4)
	v_pk_fma_f32 v[42:43], v[46:47], v[66:67], v[42:43]
	ds_read_b128 v[66:69], v117 offset:33328
	v_lshlrev_b32_e32 v30, 16, v31
	v_and_b32_e32 v31, 0xffff0000, v31
	v_pk_fma_f32 v[22:23], v[48:49], v[26:27], v[22:23]
	v_lshlrev_b32_e32 v166, 16, v34
	v_and_b32_e32 v167, 0xffff0000, v34
	s_waitcnt lgkmcnt(3)
	v_pk_fma_f32 v[42:43], v[54:55], v[74:75], v[42:43]
	ds_read_b128 v[74:77], v117 offset:33584
	v_lshlrev_b32_e32 v34, 16, v35
	v_and_b32_e32 v35, 0xffff0000, v35
	v_pk_fma_f32 v[22:23], v[56:57], v[30:31], v[22:23]
	v_lshlrev_b32_e32 v30, 16, v28
	s_waitcnt lgkmcnt(3)
	v_pk_fma_f32 v[26:27], v[60:61], v[34:35], v[22:23]
	v_lshlrev_b32_e32 v22, 16, v24
	v_and_b32_e32 v23, 0xffff0000, v24
	v_and_b32_e32 v31, 0xffff0000, v28
	v_pk_fma_f32 v[22:23], v[38:39], v[22:23], v[50:51]
	v_lshlrev_b32_e32 v34, 16, v32
	v_and_b32_e32 v35, 0xffff0000, v32
	s_waitcnt lgkmcnt(2)
	v_pk_fma_f32 v[22:23], v[62:63], v[30:31], v[22:23]
	v_lshlrev_b32_e32 v44, 16, v36
	v_and_b32_e32 v45, 0xffff0000, v36
	s_waitcnt lgkmcnt(1)
	v_pk_fma_f32 v[22:23], v[66:67], v[34:35], v[22:23]
	v_lshlrev_b32_e32 v24, 16, v29
	s_waitcnt lgkmcnt(0)
	v_pk_fma_f32 v[30:31], v[74:75], v[44:45], v[22:23]
	v_lshlrev_b32_e32 v22, 16, v25
	v_and_b32_e32 v23, 0xffff0000, v25
	v_and_b32_e32 v25, 0xffff0000, v29
	v_pk_fma_f32 v[22:23], v[40:41], v[22:23], v[52:53]
	v_lshlrev_b32_e32 v28, 16, v33
	v_and_b32_e32 v29, 0xffff0000, v33
	v_pk_fma_f32 v[22:23], v[64:65], v[24:25], v[22:23]
	v_lshlrev_b32_e32 v32, 16, v37
	v_and_b32_e32 v33, 0xffff0000, v37
	v_pk_fma_f32 v[22:23], v[68:69], v[28:29], v[22:23]
	v_pk_fma_f32 v[42:43], v[58:59], v[166:167], v[42:43]
	v_pk_fma_f32 v[28:29], v[76:77], v[32:33], v[22:23]
	v_cvt_pk_bf16_f32 v22, v162, v163
	v_cvt_pk_bf16_f32 v23, v164, v165
	v_cvt_pk_bf16_f32 v24, v158, v159
	v_cvt_pk_bf16_f32 v25, v160, v161
	ds_write_b128 v128, v[22:25] offset:44544
	v_cvt_pk_bf16_f32 v22, v42, v43
	v_cvt_pk_bf16_f32 v23, v26, v27
	v_cvt_pk_bf16_f32 v24, v30, v31
	v_cvt_pk_bf16_f32 v25, v28, v29
	ds_write_b128 v129, v[22:25] offset:44544
	v_add_u32_e32 v22, v119, v120
	s_waitcnt lgkmcnt(0)
	s_barrier
; DEVI float bf2f(bf16_t h) { return __uint_as_float(((unsigned)h) << 16); }
; template <bool PASS_C>
; DEVI void lru_item(const P& p, int item, int next_item, uint4& u0, uint4& u1, uint4& u2, float& cpre, char* smem) {
;     ...
;     f32x4 acc[16];
; #pragma unroll
;     for (int n = 0; n < 16; ++n) acc[n] = (f32x4){0.f, 0.f, 0.f, 0.f};
;     {
;         bf16x8 af[2];
; #pragma unroll
;         for (int kk = 0; kk < 2; ++kk) af[kk] = *(const bf16x8*)(ucb + (16 * w + fr) * 128 + (((kk * 4 + fq) ^ (fr & 7)) << 4));
; #pragma unroll
;         for (int n = 0; n < 16; ++n)
; #pragma unroll
;             for (int kk = 0; kk < 2; ++kk) {
;                 const bf16x8 bfr = *(const bf16x8*)(smem + (16 * n + fr) * 128 + (((kk * 4 + fq) ^ (fr & 7)) << 4));
;                 acc[n] = __builtin_amdgcn_mfma_f32_16x16x32_bf16(af[kk], bfr, acc[n], 0, 0, 0);
;             }
;     }
;     float av[4][2][4], bv[4][2][4], apre[4][2], bpre[4][2];
; #pragma unroll
;     for (int nn = 0; nn < 4; ++nn) {
;         const int ch = 16 * nn + fr;
;         float uc[4];
; #pragma unroll
;         for (int j = 0; j < 4; ++j) {
;             const int tl = 16 * w + 4 * fq + j;
;             uc[j] = bf2f(*(const bf16_t*)(ucb + tl * 128 + ((((ch >> 3)) ^ (tl & 7)) << 4) + (ch & 7) * 2));
;         }
; #pragma unroll
;         for (int d = 0; d < 2; ++d) {
;             const float ba = prm[(5 + d) * 64 + ch], bx = prm[(7 + d) * 64 + ch], nsp8 = prm[(9 + d) * 64 + ch];
	v_add_u32_e32 v87, v118, v120
	v_add_u32_e32 v30, v119, v121
	v_add_u32_e32 v89, v118, v121
	ds_read_b128 v[26:29], v22 offset:44544
	ds_read_b128 v[158:161], v30 offset:44544
	ds_read_b32 v93, v122 offset:35072
	ds_read_b128 v[232:235], v87
	ds_read_b128 v[236:239], v89
	ds_read_b128 v[240:243], v87 offset:2048
	ds_read_b128 v[244:247], v89 offset:2048
	ds_read_b128 v[248:251], v87 offset:4096
	ds_read_b128 v[192:195], v89 offset:4096
	ds_read_b128 v[252:255], v87 offset:6144
	ds_read_b128 v[218:221], v89 offset:6144
	s_waitcnt lgkmcnt(4)
	v_mfma_f32_16x16x32_bf16 v[166:169], v[26:29], v[232:235], 0
	ds_read_b128 v[222:225], v87 offset:8192
	ds_read_b128 v[226:229], v89 offset:8192
	ds_read_b128 v[162:165], v87 offset:10240
	ds_read_b128 v[188:191], v89 offset:10240
	v_mfma_f32_16x16x32_bf16 v[62:65], v[26:29], v[240:243], 0
	v_mfma_f32_16x16x32_bf16 v[166:169], v[158:161], v[236:239], v[166:169]
	v_mfma_f32_16x16x32_bf16 v[62:65], v[158:161], v[244:247], v[62:65]
	s_waitcnt lgkmcnt(4)
	v_mfma_f32_16x16x32_bf16 v[46:49], v[26:29], v[248:251], 0
	ds_read_b128 v[232:235], v87 offset:12288
	ds_read_b128 v[236:239], v89 offset:12288
	ds_read_b128 v[240:243], v87 offset:14336
	ds_read_b128 v[244:247], v89 offset:14336
	v_mfma_f32_16x16x32_bf16 v[30:33], v[26:29], v[252:255], 0
	v_mfma_f32_16x16x32_bf16 v[46:49], v[158:161], v[192:195], v[46:49]
	v_mfma_f32_16x16x32_bf16 v[30:33], v[158:161], v[218:221], v[30:33]
	s_waitcnt lgkmcnt(4)
	v_mfma_f32_16x16x32_bf16 v[184:187], v[26:29], v[222:225], 0
	ds_read_b128 v[248:251], v87 offset:16384
	ds_read_b128 v[192:195], v89 offset:16384
	ds_read_b128 v[252:255], v87 offset:18432
	ds_read_b128 v[218:221], v89 offset:18432
	v_mfma_f32_16x16x32_bf16 v[66:69], v[26:29], v[162:165], 0
	v_mfma_f32_16x16x32_bf16 v[184:187], v[158:161], v[226:229], v[184:187]
	v_mfma_f32_16x16x32_bf16 v[66:69], v[158:161], v[188:191], v[66:69]
	s_waitcnt lgkmcnt(4)
	v_mfma_f32_16x16x32_bf16 v[50:53], v[26:29], v[232:235], 0
	ds_read_b128 v[222:225], v87 offset:20480
	ds_read_b128 v[226:229], v89 offset:20480
	ds_read_b128 v[162:165], v87 offset:22528
	ds_read_b128 v[188:191], v89 offset:22528
	v_mfma_f32_16x16x32_bf16 v[34:37], v[26:29], v[240:243], 0
	v_mfma_f32_16x16x32_bf16 v[50:53], v[158:161], v[236:239], v[50:53]
	v_mfma_f32_16x16x32_bf16 v[34:37], v[158:161], v[244:247], v[34:37]
	s_waitcnt lgkmcnt(4)
	v_mfma_f32_16x16x32_bf16 v[70:73], v[26:29], v[248:251], 0
	ds_read_b128 v[232:235], v87 offset:24576
	ds_read_b128 v[236:239], v89 offset:24576
	ds_read_b128 v[240:243], v87 offset:26624
	ds_read_b128 v[244:247], v89 offset:26624
	v_mfma_f32_16x16x32_bf16 v[54:57], v[26:29], v[252:255], 0
	v_mfma_f32_16x16x32_bf16 v[70:73], v[158:161], v[192:195], v[70:73]
	v_mfma_f32_16x16x32_bf16 v[54:57], v[158:161], v[218:221], v[54:57]
	s_waitcnt lgkmcnt(4)
	v_mfma_f32_16x16x32_bf16 v[38:41], v[26:29], v[222:225], 0
	ds_read_b128 v[248:251], v87 offset:28672
	ds_read_b128 v[252:255], v87 offset:30720
	ds_read_b128 v[192:195], v89 offset:28672
	v_mfma_f32_16x16x32_bf16 v[22:25], v[26:29], v[162:165], 0
	v_mfma_f32_16x16x32_bf16 v[38:41], v[158:161], v[226:229], v[38:41]
	v_mfma_f32_16x16x32_bf16 v[22:25], v[158:161], v[188:191], v[22:25]
	s_waitcnt lgkmcnt(3)
	v_mfma_f32_16x16x32_bf16 v[74:77], v[26:29], v[232:235], 0
	v_mfma_f32_16x16x32_bf16 v[58:61], v[26:29], v[240:243], 0
	v_mfma_f32_16x16x32_bf16 v[74:77], v[158:161], v[236:239], v[74:77]
	v_mfma_f32_16x16x32_bf16 v[58:61], v[158:161], v[244:247], v[58:61]
	s_waitcnt lgkmcnt(1)
	v_mfma_f32_16x16x32_bf16 v[42:45], v[26:29], v[248:251], 0
	v_mfma_f32_16x16x32_bf16 v[26:29], v[26:29], v[252:255], 0
	ds_read_b128 v[162:165], v89 offset:30720
	ds_read2st64_b32 v[170:171], v122 offset0:133 offset1:135
	ds_read_u16 v246, v130 offset:44544
	ds_read_u16 v247, v131 offset:44544
	ds_read_u16 v248, v132 offset:44544
	ds_read_u16 v249, v133 offset:44544
	ds_read2st64_b32 v[232:233], v122 offset0:134 offset1:136
	ds_read_b32 v250, v122 offset:35328
	v_add_u32_e32 v217, 64, v122
	ds_read2st64_b32 v[234:235], v217 offset0:133 offset1:135
	ds_read_u16 v251, v134 offset:44544
	ds_read_u16 v252, v135 offset:44544
	ds_read_u16 v253, v136 offset:44544
	ds_read_u16 v254, v137 offset:44544
	ds_read_b32 v255, v122 offset:35136
	v_add_u32_e32 v217, 64, v122
	ds_read2st64_b32 v[236:237], v217 offset0:134 offset1:136
	ds_read_b32 v218, v122 offset:35392
	v_add_u32_e32 v217, 0x80, v122
	ds_read2st64_b32 v[238:239], v217 offset0:133 offset1:135
	ds_read_u16 v219, v138 offset:44544
	ds_read_u16 v220, v139 offset:44544
	ds_read_u16 v221, v140 offset:44544
	ds_read_u16 v222, v141 offset:44544
	ds_read_b32 v223, v122 offset:35200
	v_add_u32_e32 v217, 0x80, v122
	ds_read2st64_b32 v[240:241], v217 offset0:134 offset1:136
	ds_read_b32 v224, v122 offset:35456
	v_add_u32_e32 v217, 0xc0, v122
	ds_read2st64_b32 v[242:243], v217 offset0:133 offset1:135
	ds_read_u16 v225, v142 offset:44544
	ds_read_u16 v226, v143 offset:44544
	ds_read_u16 v227, v144 offset:44544
	ds_read_u16 v228, v145 offset:44544
	ds_read_b32 v229, v122 offset:35264
	v_add_u32_e32 v217, 0xc0, v122
	ds_read2st64_b32 v[244:245], v217 offset0:134 offset1:136
	ds_read_b32 v231, v122 offset:35520
	s_waitcnt lgkmcnt(0)
; template <bool PASS_C>
; DEVI void lru_item(const P& p, int item, int next_item, uint4& u0, uint4& u1, uint4& u2, float& cpre, char* smem) {
;     ...
; #pragma unroll
;     for (int nn = 0; nn < 4; ++nn) {
;         const int ch = 16 * nn + fr;
;         float uc[4];
; #pragma unroll
;         for (int j = 0; j < 4; ++j) {
;             const int tl = 16 * w + 4 * fq + j;
;             uc[j] = bf2f(*(const bf16_t*)(ucb + tl * 128 + ((((ch >> 3)) ^ (tl & 7)) << 4) + (ch & 7) * 2));
;         }
; #pragma unroll
;         for (int d = 0; d < 2; ++d) {
;             const float ba = prm[(5 + d) * 64 + ch], bx = prm[(7 + d) * 64 + ch], nsp8 = prm[(9 + d) * 64 + ch];
; #pragma unroll
;             for (int j = 0; j < 4; ++j) {
;                 const float r = __builtin_amdgcn_rcpf(1.0f + __builtin_amdgcn_exp2f(__builtin_fmaf(acc[(2 * d) * 4 + nn][j], -LOG2E, ba)));
;                 const float ig = __builtin_amdgcn_rcpf(1.0f + __builtin_amdgcn_exp2f(__builtin_fmaf(acc[(2 * d + 1) * 4 + nn][j], -LOG2E, bx)));
;                 const float a_ = __builtin_amdgcn_exp2f(nsp8 * r);
;                 av[nn][d][j] = a_;
;                 bv[nn][d][j] = __builtin_amdgcn_sqrtf(__builtin_fmaf(-a_, a_, 1.0f)) * ig * uc[j];
;             }
;             float A = 1.f, Bq = 0.f;
;             if (d == 0) {
; #pragma unroll
;                 for (int j = 0; j < 4; ++j) { Bq = av[nn][d][j] * Bq + bv[nn][d][j]; A *= av[nn][d][j]; }
;             } else {
; #pragma unroll
;                 for (int j = 3; j >= 0; --j) { Bq = av[nn][d][j] * Bq + bv[nn][d][j]; A *= av[nn][d][j]; }
;             }
;             float Ag[4], Bg[4];
;             rowgather4(A, Ag); rowgather4(Bq, Bg);
;             float AW = 1.f, BW = 0.f, AP = 1.f, BP = 0.f;
;             if (d == 0) {
; #pragma unroll
;                 for (int g = 0; g < 4; ++g) {
;                     if (g == fq) { AP = AW; BP = BW; }
;                     BW = Ag[g] * BW + Bg[g]; AW *= Ag[g];
;                 }
;             } else {
; #pragma unroll
;                 for (int g = 3; g >= 0; --g) {
;                     if (g == fq) { AP = AW; BP = BW; }
;                     BW = Ag[g] * BW + Bg[g]; AW *= Ag[g];
;                 }
;             }
;             apre[nn][d] = AP; bpre[nn][d] = BP;
;             if (fq == 0) { wagg[((w * 2 + d) * 64 + ch) * 2 + 0] = AW; wagg[((w * 2 + d) * 64 + ch) * 2 + 1] = BW; }
;         }
	v_fmamk_f32 v95, v166, 0xbfb8aa3b, v170
	v_exp_f32_e32 v95, v95
	v_mfma_f32_16x16x32_bf16 v[42:45], v[158:161], v[192:195], v[42:45]
	v_fmamk_f32 v99, v168, 0xbfb8aa3b, v170
	v_fmamk_f32 v101, v186, 0xbfb8aa3b, v171
	v_exp_f32_e32 v99, v99
	v_mfma_f32_16x16x32_bf16 v[26:29], v[158:161], v[162:165], v[26:29]
	v_lshlrev_b32_e32 v164, 16, v246
	v_lshlrev_b32_e32 v161, 16, v247
	v_add_f32_e32 v87, 1.0, v95
	v_fmamk_f32 v89, v184, 0xbfb8aa3b, v171
	v_exp_f32_e32 v89, v89
	v_rcp_f32_e32 v87, v87
	v_lshlrev_b32_e32 v162, 16, v248
	v_add_f32_e32 v95, 1.0, v89
	v_mul_f32_e32 v87, v93, v87
	v_exp_f32_e32 v89, v87
	v_rcp_f32_e32 v87, v95
	v_fmamk_f32 v95, v167, 0xbfb8aa3b, v170
	v_exp_f32_e32 v95, v95
	v_lshlrev_b32_e32 v163, 16, v249
	v_fma_f32 v97, -v89, v89, 1.0
	v_sqrt_f32_e32 v97, v97
	v_add_f32_e32 v91, 1.0, v95
	v_rcp_f32_e32 v91, v91
	v_fmamk_f32 v95, v185, 0xbfb8aa3b, v171
	v_exp_f32_e32 v95, v95
	v_mul_f32_e32 v87, v87, v97
	v_mul_f32_e32 v91, v93, v91
	v_exp_f32_e32 v91, v91
	v_add_f32_e32 v95, 1.0, v95
	v_rcp_f32_e32 v95, v95
	v_exp_f32_e32 v101, v101
	v_fma_f32 v97, -v91, v91, 1.0
	v_sqrt_f32_e32 v97, v97
	v_fmamk_f32 v171, v187, 0xbfb8aa3b, v171
	v_exp_f32_e32 v105, v171
	v_mul_f32_e32 v87, v87, v164
	v_mul_f32_e32 v97, v95, v97
	v_add_f32_e32 v95, 1.0, v99
	v_add_f32_e32 v99, 1.0, v101
	v_fmamk_f32 v101, v169, 0xbfb8aa3b, v170
	v_exp_f32_e32 v101, v101
	v_rcp_f32_e32 v95, v95
	v_rcp_f32_e32 v99, v99
	v_add_f32_e32 v101, 1.0, v101
	v_rcp_f32_e32 v101, v101
	v_mul_f32_e32 v95, v93, v95
	v_exp_f32_e32 v95, v95
	v_mul_f32_e32 v93, v93, v101
	v_exp_f32_e32 v101, v93
	v_add_f32_e32 v93, 1.0, v105
	v_fma_f32 v103, -v95, v95, 1.0
	v_rcp_f32_e32 v105, v93
	v_fma_f32 v93, -v101, v101, 1.0
	v_sqrt_f32_e32 v103, v103
	v_sqrt_f32_e32 v157, v93
	v_mul_f32_e32 v93, v97, v161
	v_mul_f32_e32 v97, v99, v103
	v_mul_f32_e32 v99, v105, v157
	v_fma_f32 v105, 0, v89, v87
	v_mul_f32_e32 v97, v97, v162
	v_mul_f32_e32 v103, v89, v91
	v_fma_f32 v105, v91, v105, v93
	v_mul_f32_e32 v99, v99, v163
	v_mul_f32_e32 v103, v95, v103
	v_fma_f32 v105, v95, v105, v97
	v_mul_f32_e32 v103, v101, v103
	v_fma_f32 v105, v101, v105, v99
	v_mov_b32_e32 v159, v103
	v_mov_b32_e32 v157, v105
	s_nop 0
	v_permlane16_swap_b32_e32 v103, v159
	v_permlane16_swap_b32_e32 v105, v157
	v_mov_b32_e32 v160, v103
	v_mov_b32_e32 v158, v105
	s_nop 0
	v_permlane32_swap_b32_e32 v103, v160
	v_mov_b32_e32 v165, v159
	v_permlane32_swap_b32_e32 v105, v158
	v_mov_b32_e32 v166, v157
	v_permlane32_swap_b32_e32 v159, v165
	s_nop 0
	v_permlane32_swap_b32_e32 v157, v166
	v_fmac_f32_e32 v105, 0, v103
	v_fmac_f32_e32 v157, v105, v159
	v_mul_f32_e32 v159, v103, v159
	v_fmac_f32_e32 v158, v157, v160
	v_mul_f32_e32 v160, v159, v160
	s_and_saveexec_b64 s[28:29], s[10:11]
	v_mul_f32_e32 v167, v158, v165
	v_mul_f32_e32 v168, v160, v165
	v_add_f32_e32 v169, v167, v166
	ds_write_b64 v149, v[168:169] offset:52736
	s_or_b64 exec, exec, s[28:29]
	v_fmamk_f32 v70, v70, 0xbfb8aa3b, v232
	v_exp_f32_e32 v70, v70
	v_fmamk_f32 v71, v71, 0xbfb8aa3b, v232
	v_exp_f32_e32 v71, v71
	v_fmamk_f32 v74, v74, 0xbfb8aa3b, v233
	v_add_f32_e32 v70, 1.0, v70
	v_rcp_f32_e32 v70, v70
	v_add_f32_e32 v71, 1.0, v71
	v_exp_f32_e32 v74, v74
	v_rcp_f32_e32 v71, v71
	v_mul_f32_e32 v70, v250, v70
	v_exp_f32_e32 v70, v70
	v_fmamk_f32 v75, v75, 0xbfb8aa3b, v233
	v_add_f32_e32 v74, 1.0, v74
	v_mul_f32_e32 v71, v250, v71
	v_fma_f32 v168, -v70, v70, 1.0
	v_fmamk_f32 v72, v72, 0xbfb8aa3b, v232
	v_fmamk_f32 v73, v73, 0xbfb8aa3b, v232
	v_exp_f32_e32 v75, v75
	v_rcp_f32_e32 v74, v74
	v_exp_f32_e32 v71, v71
	v_sqrt_f32_e32 v168, v168
	v_exp_f32_e32 v72, v72
	v_exp_f32_e32 v73, v73
	v_add_f32_e32 v75, 1.0, v75
	v_fma_f32 v169, -v71, v71, 1.0
	v_mul_f32_e32 v74, v74, v168
	v_fmamk_f32 v76, v76, 0xbfb8aa3b, v233
	v_add_f32_e32 v72, 1.0, v72
	v_add_f32_e32 v73, 1.0, v73
	v_rcp_f32_e32 v75, v75
	v_mul_f32_e32 v74, v74, v164
	v_sqrt_f32_e32 v164, v169
	v_exp_f32_e32 v76, v76
	v_rcp_f32_e32 v72, v72
	v_rcp_f32_e32 v73, v73
	v_fmamk_f32 v167, v77, 0xbfb8aa3b, v233
	v_mul_f32_e32 v164, v75, v164
	v_add_f32_e32 v75, 1.0, v76
	v_mul_f32_e32 v72, v250, v72
	v_exp_f32_e32 v77, v167
	v_mul_f32_e32 v73, v250, v73
	v_exp_f32_e32 v72, v72
	v_rcp_f32_e32 v76, v75
	v_exp_f32_e32 v75, v73
	v_add_f32_e32 v73, 1.0, v77
	v_fma_f32 v166, -v72, v72, 1.0
	v_rcp_f32_e32 v77, v73
	v_fma_f32 v73, -v75, v75, 1.0
	v_sqrt_f32_e32 v165, v166
	v_sqrt_f32_e32 v166, v73
	v_mul_f32_e32 v73, v164, v161
	v_mul_f32_e32 v161, v75, v72
	v_mul_f32_e32 v76, v76, v165
	v_mul_f32_e32 v77, v77, v166
	v_mul_f32_e32 v77, v77, v163
	v_mul_f32_e32 v161, v71, v161
	v_mul_f32_e32 v76, v76, v162
	v_mul_f32_e32 v165, v70, v161
	v_fma_f32 v161, 0, v75, v77
	v_fma_f32 v161, v72, v161, v76
	v_fma_f32 v161, v71, v161, v73
	v_fma_f32 v168, v70, v161, v74
	v_mov_b32_e32 v167, v165
	v_mov_b32_e32 v161, v168
	s_nop 0
	v_permlane16_swap_b32_e32 v165, v167
	v_permlane16_swap_b32_e32 v168, v161
	v_mov_b32_e32 v162, v167
	v_mov_b32_e32 v164, v161
	v_mov_b32_e32 v166, v165
	v_permlane32_swap_b32_e32 v167, v162
	v_mov_b32_e32 v163, v168
	v_permlane32_swap_b32_e32 v161, v164
	v_permlane32_swap_b32_e32 v165, v166
	v_permlane32_swap_b32_e32 v168, v163
	v_fmac_f32_e32 v164, 0, v162
	v_fmac_f32_e32 v163, v164, v166
	v_mul_f32_e32 v166, v166, v162
	v_fmac_f32_e32 v161, v163, v167
	v_mul_f32_e32 v167, v166, v167
	s_and_saveexec_b64 s[28:29], s[10:11]
	v_mul_f32_e32 v169, v161, v165
	v_mul_f32_e32 v170, v167, v165
	v_add_f32_e32 v171, v169, v168
	ds_write_b64 v149, v[170:171] offset:53248
	s_or_b64 exec, exec, s[28:29]
	v_lshlrev_b32_e32 v185, 16, v251
	v_lshlrev_b32_e32 v183, 16, v252
	v_lshlrev_b32_e32 v177, 16, v253
; template <bool PASS_C>
; DEVI void lru_item(const P& p, int item, int next_item, uint4& u0, uint4& u1, uint4& u2, float& cpre, char* smem) {
;     ...
; #pragma unroll
;     for (int nn = 0; nn < 4; ++nn) {
;         const int ch = 16 * nn + fr;
;         float uc[4];
; #pragma unroll
;         for (int j = 0; j < 4; ++j) {
;             const int tl = 16 * w + 4 * fq + j;
;             uc[j] = bf2f(*(const bf16_t*)(ucb + tl * 128 + ((((ch >> 3)) ^ (tl & 7)) << 4) + (ch & 7) * 2));
;         }
; #pragma unroll
;         for (int d = 0; d < 2; ++d) {
;             const float ba = prm[(5 + d) * 64 + ch], bx = prm[(7 + d) * 64 + ch], nsp8 = prm[(9 + d) * 64 + ch];
; #pragma unroll
;             for (int j = 0; j < 4; ++j) {
;                 const float r = __builtin_amdgcn_rcpf(1.0f + __builtin_amdgcn_exp2f(__builtin_fmaf(acc[(2 * d) * 4 + nn][j], -LOG2E, ba)));
;                 const float ig = __builtin_amdgcn_rcpf(1.0f + __builtin_amdgcn_exp2f(__builtin_fmaf(acc[(2 * d + 1) * 4 + nn][j], -LOG2E, bx)));
;                 const float a_ = __builtin_amdgcn_exp2f(nsp8 * r);
;                 av[nn][d][j] = a_;
;                 bv[nn][d][j] = __builtin_amdgcn_sqrtf(__builtin_fmaf(-a_, a_, 1.0f)) * ig * uc[j];
;             }
;             float A = 1.f, Bq = 0.f;
;             if (d == 0) {
; #pragma unroll
;                 for (int j = 0; j < 4; ++j) { Bq = av[nn][d][j] * Bq + bv[nn][d][j]; A *= av[nn][d][j]; }
;             } else {
; #pragma unroll
;                 for (int j = 3; j >= 0; --j) { Bq = av[nn][d][j] * Bq + bv[nn][d][j]; A *= av[nn][d][j]; }
;             }
;             float Ag[4], Bg[4];
;             rowgather4(A, Ag); rowgather4(Bq, Bg);
;             float AW = 1.f, BW = 0.f, AP = 1.f, BP = 0.f;
;             if (d == 0) {
; #pragma unroll
;                 for (int g = 0; g < 4; ++g) {
;                     if (g == fq) { AP = AW; BP = BW; }
;                     BW = Ag[g] * BW + Bg[g]; AW *= Ag[g];
;                 }
;             } else {
; #pragma unroll
;                 for (int g = 3; g >= 0; --g) {
;                     if (g == fq) { AP = AW; BP = BW; }
;                     BW = Ag[g] * BW + Bg[g]; AW *= Ag[g];
;                 }
;             }
;             apre[nn][d] = AP; bpre[nn][d] = BP;
;             if (fq == 0) { wagg[((w * 2 + d) * 64 + ch) * 2 + 0] = AW; wagg[((w * 2 + d) * 64 + ch) * 2 + 1] = BW; }
;         }
	v_fmamk_f32 v62, v62, 0xbfb8aa3b, v234
	v_exp_f32_e32 v62, v62
	v_fmamk_f32 v63, v63, 0xbfb8aa3b, v234
	v_fmamk_f32 v66, v66, 0xbfb8aa3b, v235
	v_exp_f32_e32 v63, v63
	v_add_f32_e32 v62, 1.0, v62
	v_rcp_f32_e32 v62, v62
	v_exp_f32_e32 v66, v66
	v_add_f32_e32 v63, 1.0, v63
	v_rcp_f32_e32 v63, v63
	v_mul_f32_e32 v62, v255, v62
	v_add_f32_e32 v165, 1.0, v66
	v_exp_f32_e32 v66, v62
	v_rcp_f32_e32 v62, v165
	v_fmamk_f32 v67, v67, 0xbfb8aa3b, v235
	v_mul_f32_e32 v63, v255, v63
	v_fma_f32 v165, -v66, v66, 1.0
	v_sqrt_f32_e32 v165, v165
	v_exp_f32_e32 v67, v67
	v_exp_f32_e32 v63, v63
	v_fmamk_f32 v64, v64, 0xbfb8aa3b, v234
	v_exp_f32_e32 v64, v64
	v_mul_f32_e32 v62, v62, v165
	v_add_f32_e32 v67, 1.0, v67
	v_fma_f32 v165, -v63, v63, 1.0
	v_rcp_f32_e32 v67, v67
	v_sqrt_f32_e32 v165, v165
	v_add_f32_e32 v64, 1.0, v64
	v_rcp_f32_e32 v64, v64
	v_fmamk_f32 v65, v65, 0xbfb8aa3b, v234
	v_mul_f32_e32 v67, v67, v165
	v_exp_f32_e32 v165, v65
	v_mul_f32_e32 v64, v255, v64
	v_exp_f32_e32 v65, v64
	v_fmamk_f32 v68, v68, 0xbfb8aa3b, v235
	v_add_f32_e32 v64, 1.0, v165
	v_rcp_f32_e32 v64, v64
	v_fmamk_f32 v169, v69, 0xbfb8aa3b, v235
	v_exp_f32_e32 v168, v169
	v_exp_f32_e32 v68, v68
	v_mul_f32_e32 v64, v255, v64
	v_exp_f32_e32 v69, v64
	v_add_f32_e32 v64, 1.0, v168
	v_add_f32_e32 v68, 1.0, v68
	v_fma_f32 v165, -v65, v65, 1.0
	v_rcp_f32_e32 v168, v64
	v_fma_f32 v64, -v69, v69, 1.0
	v_rcp_f32_e32 v68, v68
	v_sqrt_f32_e32 v165, v165
	v_sqrt_f32_e32 v169, v64
	v_mul_f32_e32 v62, v62, v185
	v_mul_f32_e32 v64, v67, v183
	v_mul_f32_e32 v67, v68, v165
	v_mul_f32_e32 v68, v168, v169
	v_fma_f32 v168, 0, v66, v62
	v_lshlrev_b32_e32 v184, 16, v254
	v_mul_f32_e32 v67, v67, v177
	v_mul_f32_e32 v165, v66, v63
	v_fma_f32 v168, v63, v168, v64
	v_mul_f32_e32 v68, v68, v184
	v_mul_f32_e32 v165, v65, v165
	v_fma_f32 v168, v65, v168, v67
	v_mul_f32_e32 v165, v69, v165
	v_fma_f32 v168, v69, v168, v68
	v_mov_b32_e32 v171, v165
	v_mov_b32_e32 v169, v168
	s_nop 0
	v_permlane16_swap_b32_e32 v165, v171
	v_permlane16_swap_b32_e32 v168, v169
	v_mov_b32_e32 v173, v165
	v_mov_b32_e32 v170, v168
	s_nop 0
	v_permlane32_swap_b32_e32 v165, v173
	v_mov_b32_e32 v187, v171
	v_permlane32_swap_b32_e32 v168, v170
	v_mov_b32_e32 v188, v169
	v_permlane32_swap_b32_e32 v171, v187
	s_nop 0
	v_permlane32_swap_b32_e32 v169, v188
	v_fmac_f32_e32 v168, 0, v165
	v_fmac_f32_e32 v169, v168, v171
	v_mul_f32_e32 v171, v165, v171
	v_fmac_f32_e32 v170, v169, v173
	v_mul_f32_e32 v173, v171, v173
	s_and_saveexec_b64 s[28:29], s[10:11]
	v_mul_f32_e32 v189, v170, v187
	v_mul_f32_e32 v190, v173, v187
	v_add_f32_e32 v191, v189, v188
	ds_write_b64 v150, v[190:191] offset:52736
	s_or_b64 exec, exec, s[28:29]
	v_fmamk_f32 v54, v54, 0xbfb8aa3b, v236
	v_exp_f32_e32 v54, v54
	v_fmamk_f32 v55, v55, 0xbfb8aa3b, v236
	v_exp_f32_e32 v55, v55
	v_fmamk_f32 v58, v58, 0xbfb8aa3b, v237
	v_add_f32_e32 v54, 1.0, v54
	v_rcp_f32_e32 v54, v54
	v_add_f32_e32 v55, 1.0, v55
	v_exp_f32_e32 v58, v58
	v_rcp_f32_e32 v55, v55
	v_mul_f32_e32 v54, v218, v54
	v_exp_f32_e32 v54, v54
	v_fmamk_f32 v56, v56, 0xbfb8aa3b, v236
	v_fmamk_f32 v59, v59, 0xbfb8aa3b, v237
	v_add_f32_e32 v58, 1.0, v58
	v_mul_f32_e32 v55, v218, v55
	v_fma_f32 v189, -v54, v54, 1.0
	v_exp_f32_e32 v56, v56
	v_fmamk_f32 v57, v57, 0xbfb8aa3b, v236
	v_exp_f32_e32 v59, v59
	v_rcp_f32_e32 v58, v58
	v_exp_f32_e32 v55, v55
	v_sqrt_f32_e32 v189, v189
	v_exp_f32_e32 v57, v57
	v_add_f32_e32 v56, 1.0, v56
	v_add_f32_e32 v59, 1.0, v59
	v_fma_f32 v190, -v55, v55, 1.0
	v_mul_f32_e32 v58, v58, v189
	v_fmamk_f32 v60, v60, 0xbfb8aa3b, v237
	v_rcp_f32_e32 v56, v56
	v_add_f32_e32 v57, 1.0, v57
	v_rcp_f32_e32 v59, v59
	v_mul_f32_e32 v58, v58, v185
	v_sqrt_f32_e32 v185, v190
	v_exp_f32_e32 v60, v60
	v_rcp_f32_e32 v57, v57
	v_mul_f32_e32 v56, v218, v56
	v_fmamk_f32 v187, v61, 0xbfb8aa3b, v237
	v_mul_f32_e32 v185, v59, v185
	v_add_f32_e32 v59, 1.0, v60
	v_exp_f32_e32 v56, v56
	v_exp_f32_e32 v61, v187
	v_mul_f32_e32 v57, v218, v57
	v_rcp_f32_e32 v60, v59
	v_exp_f32_e32 v59, v57
	v_fma_f32 v186, -v56, v56, 1.0
	v_add_f32_e32 v57, 1.0, v61
	v_sqrt_f32_e32 v186, v186
	v_rcp_f32_e32 v61, v57
	v_fma_f32 v57, -v59, v59, 1.0
	v_sqrt_f32_e32 v187, v57
	v_mul_f32_e32 v60, v60, v186
	v_mul_f32_e32 v60, v60, v177
	v_mul_f32_e32 v177, v59, v56
	v_mul_f32_e32 v61, v61, v187
	v_mul_f32_e32 v61, v61, v184
	v_mul_f32_e32 v177, v55, v177
	v_mul_f32_e32 v186, v54, v177
	v_fma_f32 v177, 0, v59, v61
	v_mul_f32_e32 v57, v185, v183
	v_fma_f32 v177, v56, v177, v60
	v_fma_f32 v177, v55, v177, v57
	v_fma_f32 v189, v54, v177, v58
	v_mov_b32_e32 v188, v186
	v_mov_b32_e32 v177, v189
	s_nop 0
	v_permlane16_swap_b32_e32 v186, v188
	v_permlane16_swap_b32_e32 v189, v177
	v_mov_b32_e32 v183, v188
	v_mov_b32_e32 v185, v177
	v_mov_b32_e32 v187, v186
	v_permlane32_swap_b32_e32 v188, v183
	v_mov_b32_e32 v184, v189
	v_permlane32_swap_b32_e32 v177, v185
	v_permlane32_swap_b32_e32 v186, v187
	v_permlane32_swap_b32_e32 v189, v184
	v_fmac_f32_e32 v185, 0, v183
	v_fmac_f32_e32 v184, v185, v187
	v_mul_f32_e32 v187, v187, v183
	v_fmac_f32_e32 v177, v184, v188
	v_mul_f32_e32 v188, v187, v188
	s_and_saveexec_b64 s[28:29], s[10:11]
	v_mul_f32_e32 v191, v177, v186
	v_mul_f32_e32 v190, v188, v186
	v_add_f32_e32 v191, v191, v189
	ds_write_b64 v150, v[190:191] offset:53248
	s_or_b64 exec, exec, s[28:29]
	v_lshlrev_b32_e32 v197, 16, v219
	v_lshlrev_b32_e32 v195, 16, v220
	v_lshlrev_b32_e32 v194, 16, v221
	v_fmamk_f32 v46, v46, 0xbfb8aa3b, v238
	v_exp_f32_e32 v46, v46
	v_fmamk_f32 v47, v47, 0xbfb8aa3b, v238
	v_fmamk_f32 v50, v50, 0xbfb8aa3b, v239
	v_exp_f32_e32 v47, v47
	v_add_f32_e32 v46, 1.0, v46
	v_rcp_f32_e32 v46, v46
	v_exp_f32_e32 v50, v50
	v_add_f32_e32 v47, 1.0, v47
; template <bool PASS_C>
; DEVI void lru_item(const P& p, int item, int next_item, uint4& u0, uint4& u1, uint4& u2, float& cpre, char* smem) {
;     ...
; #pragma unroll
;     for (int nn = 0; nn < 4; ++nn) {
;         const int ch = 16 * nn + fr;
;         float uc[4];
; #pragma unroll
;         for (int j = 0; j < 4; ++j) {
;             const int tl = 16 * w + 4 * fq + j;
;             uc[j] = bf2f(*(const bf16_t*)(ucb + tl * 128 + ((((ch >> 3)) ^ (tl & 7)) << 4) + (ch & 7) * 2));
;         }
; #pragma unroll
;         for (int d = 0; d < 2; ++d) {
;             const float ba = prm[(5 + d) * 64 + ch], bx = prm[(7 + d) * 64 + ch], nsp8 = prm[(9 + d) * 64 + ch];
; #pragma unroll
;             for (int j = 0; j < 4; ++j) {
;                 const float r = __builtin_amdgcn_rcpf(1.0f + __builtin_amdgcn_exp2f(__builtin_fmaf(acc[(2 * d) * 4 + nn][j], -LOG2E, ba)));
;                 const float ig = __builtin_amdgcn_rcpf(1.0f + __builtin_amdgcn_exp2f(__builtin_fmaf(acc[(2 * d + 1) * 4 + nn][j], -LOG2E, bx)));
;                 const float a_ = __builtin_amdgcn_exp2f(nsp8 * r);
;                 av[nn][d][j] = a_;
;                 bv[nn][d][j] = __builtin_amdgcn_sqrtf(__builtin_fmaf(-a_, a_, 1.0f)) * ig * uc[j];
;             }
;             float A = 1.f, Bq = 0.f;
;             if (d == 0) {
; #pragma unroll
;                 for (int j = 0; j < 4; ++j) { Bq = av[nn][d][j] * Bq + bv[nn][d][j]; A *= av[nn][d][j]; }
;             } else {
; #pragma unroll
;                 for (int j = 3; j >= 0; --j) { Bq = av[nn][d][j] * Bq + bv[nn][d][j]; A *= av[nn][d][j]; }
;             }
;             float Ag[4], Bg[4];
;             rowgather4(A, Ag); rowgather4(Bq, Bg);
;             float AW = 1.f, BW = 0.f, AP = 1.f, BP = 0.f;
;             if (d == 0) {
; #pragma unroll
;                 for (int g = 0; g < 4; ++g) {
;                     if (g == fq) { AP = AW; BP = BW; }
;                     BW = Ag[g] * BW + Bg[g]; AW *= Ag[g];
;                 }
;             } else {
; #pragma unroll
;                 for (int g = 3; g >= 0; --g) {
;                     if (g == fq) { AP = AW; BP = BW; }
;                     BW = Ag[g] * BW + Bg[g]; AW *= Ag[g];
;                 }
;             }
;             apre[nn][d] = AP; bpre[nn][d] = BP;
;             if (fq == 0) { wagg[((w * 2 + d) * 64 + ch) * 2 + 0] = AW; wagg[((w * 2 + d) * 64 + ch) * 2 + 1] = BW; }
;         }
	v_rcp_f32_e32 v47, v47
	v_mul_f32_e32 v46, v223, v46
	v_add_f32_e32 v186, 1.0, v50
	v_exp_f32_e32 v50, v46
	v_rcp_f32_e32 v46, v186
	v_fmamk_f32 v51, v51, 0xbfb8aa3b, v239
	v_mul_f32_e32 v47, v223, v47
	v_fma_f32 v186, -v50, v50, 1.0
	v_sqrt_f32_e32 v186, v186
	v_exp_f32_e32 v51, v51
	v_exp_f32_e32 v47, v47
	v_fmamk_f32 v48, v48, 0xbfb8aa3b, v238
	v_exp_f32_e32 v48, v48
	v_mul_f32_e32 v46, v46, v186
	v_add_f32_e32 v51, 1.0, v51
	v_fma_f32 v186, -v47, v47, 1.0
	v_rcp_f32_e32 v51, v51
	v_sqrt_f32_e32 v186, v186
	v_add_f32_e32 v48, 1.0, v48
	v_rcp_f32_e32 v48, v48
	v_fmamk_f32 v49, v49, 0xbfb8aa3b, v238
	v_mul_f32_e32 v51, v51, v186
	v_exp_f32_e32 v186, v49
	v_mul_f32_e32 v48, v223, v48
	v_exp_f32_e32 v49, v48
	v_fmamk_f32 v52, v52, 0xbfb8aa3b, v239
	v_add_f32_e32 v48, 1.0, v186
	v_rcp_f32_e32 v48, v48
	v_fmamk_f32 v191, v53, 0xbfb8aa3b, v239
	v_exp_f32_e32 v189, v191
	v_exp_f32_e32 v52, v52
	v_mul_f32_e32 v48, v223, v48
	v_exp_f32_e32 v53, v48
	v_add_f32_e32 v48, 1.0, v189
	v_add_f32_e32 v52, 1.0, v52
	v_fma_f32 v186, -v49, v49, 1.0
	v_rcp_f32_e32 v189, v48
	v_fma_f32 v48, -v53, v53, 1.0
	v_rcp_f32_e32 v52, v52
	v_sqrt_f32_e32 v186, v186
	v_sqrt_f32_e32 v190, v48
	v_mul_f32_e32 v46, v46, v197
	v_mul_f32_e32 v48, v51, v195
	v_mul_f32_e32 v51, v52, v186
	v_mul_f32_e32 v52, v189, v190
	v_fma_f32 v189, 0, v50, v46
	v_lshlrev_b32_e32 v196, 16, v222
	v_mul_f32_e32 v51, v51, v194
	v_mul_f32_e32 v186, v50, v47
	v_fma_f32 v189, v47, v189, v48
	v_mul_f32_e32 v52, v52, v196
	v_mul_f32_e32 v186, v49, v186
	v_fma_f32 v189, v49, v189, v51
	v_mul_f32_e32 v186, v53, v186
	v_fma_f32 v189, v53, v189, v52
	v_mov_b32_e32 v192, v186
	v_mov_b32_e32 v190, v189
	s_nop 0
	v_permlane16_swap_b32_e32 v186, v192
	v_permlane16_swap_b32_e32 v189, v190
	v_mov_b32_e32 v193, v186
	v_mov_b32_e32 v191, v189
	s_nop 0
	v_permlane32_swap_b32_e32 v186, v193
	v_mov_b32_e32 v199, v192
	v_permlane32_swap_b32_e32 v189, v191
	v_mov_b32_e32 v200, v190
	v_permlane32_swap_b32_e32 v192, v199
	s_nop 0
	v_permlane32_swap_b32_e32 v190, v200
	v_fmac_f32_e32 v189, 0, v186
	v_fmac_f32_e32 v190, v189, v192
	v_mul_f32_e32 v192, v186, v192
	v_fmac_f32_e32 v191, v190, v193
	v_mul_f32_e32 v193, v192, v193
	s_and_saveexec_b64 s[28:29], s[10:11]
	v_mul_f32_e32 v201, v191, v199
	v_mul_f32_e32 v202, v193, v199
	v_add_f32_e32 v203, v201, v200
	ds_write_b64 v151, v[202:203] offset:52736
	s_or_b64 exec, exec, s[28:29]
	v_fmamk_f32 v38, v38, 0xbfb8aa3b, v240
	v_exp_f32_e32 v38, v38
	v_fmamk_f32 v39, v39, 0xbfb8aa3b, v240
	v_exp_f32_e32 v39, v39
	v_fmamk_f32 v42, v42, 0xbfb8aa3b, v241
	v_add_f32_e32 v38, 1.0, v38
	v_rcp_f32_e32 v38, v38
	v_add_f32_e32 v39, 1.0, v39
	v_exp_f32_e32 v42, v42
	v_rcp_f32_e32 v39, v39
	v_mul_f32_e32 v38, v224, v38
	v_exp_f32_e32 v38, v38
	v_fmamk_f32 v40, v40, 0xbfb8aa3b, v240
	v_fmamk_f32 v43, v43, 0xbfb8aa3b, v241
	v_add_f32_e32 v42, 1.0, v42
	v_mul_f32_e32 v39, v224, v39
	v_fma_f32 v201, -v38, v38, 1.0
	v_exp_f32_e32 v40, v40
	v_fmamk_f32 v41, v41, 0xbfb8aa3b, v240
	v_exp_f32_e32 v43, v43
	v_rcp_f32_e32 v42, v42
	v_exp_f32_e32 v39, v39
	v_sqrt_f32_e32 v201, v201
	v_exp_f32_e32 v41, v41
	v_add_f32_e32 v40, 1.0, v40
	v_add_f32_e32 v43, 1.0, v43
	v_fma_f32 v202, -v39, v39, 1.0
	v_mul_f32_e32 v42, v42, v201
	v_fmamk_f32 v44, v44, 0xbfb8aa3b, v241
	v_rcp_f32_e32 v40, v40
	v_add_f32_e32 v41, 1.0, v41
	v_rcp_f32_e32 v43, v43
	v_mul_f32_e32 v42, v42, v197
	v_sqrt_f32_e32 v197, v202
	v_exp_f32_e32 v44, v44
	v_rcp_f32_e32 v41, v41
	v_mul_f32_e32 v40, v224, v40
	v_fmamk_f32 v199, v45, 0xbfb8aa3b, v241
	v_mul_f32_e32 v197, v43, v197
	v_add_f32_e32 v43, 1.0, v44
	v_exp_f32_e32 v40, v40
	v_exp_f32_e32 v45, v199
	v_mul_f32_e32 v41, v224, v41
	v_rcp_f32_e32 v44, v43
	v_exp_f32_e32 v43, v41
	v_fma_f32 v198, -v40, v40, 1.0
	v_add_f32_e32 v41, 1.0, v45
	v_sqrt_f32_e32 v198, v198
	v_rcp_f32_e32 v45, v41
	v_fma_f32 v41, -v43, v43, 1.0
	v_sqrt_f32_e32 v199, v41
	v_mul_f32_e32 v44, v44, v198
	v_mul_f32_e32 v44, v44, v194
	v_mul_f32_e32 v194, v43, v40
	v_mul_f32_e32 v45, v45, v199
	v_mul_f32_e32 v45, v45, v196
	v_mul_f32_e32 v194, v39, v194
	v_mul_f32_e32 v198, v38, v194
	v_fma_f32 v194, 0, v43, v45
	v_mul_f32_e32 v41, v197, v195
	v_fma_f32 v194, v40, v194, v44
	v_fma_f32 v194, v39, v194, v41
	v_fma_f32 v200, v38, v194, v42
	v_mov_b32_e32 v201, v198
	v_mov_b32_e32 v194, v200
	s_nop 0
	v_permlane16_swap_b32_e32 v198, v201
	v_permlane16_swap_b32_e32 v200, v194
	v_mov_b32_e32 v195, v201
	v_mov_b32_e32 v197, v194
	v_mov_b32_e32 v199, v198
	v_permlane32_swap_b32_e32 v201, v195
	v_mov_b32_e32 v196, v200
	v_permlane32_swap_b32_e32 v194, v197
	v_permlane32_swap_b32_e32 v198, v199
	v_permlane32_swap_b32_e32 v200, v196
	v_fmac_f32_e32 v197, 0, v195
	v_fmac_f32_e32 v196, v197, v199
	v_mul_f32_e32 v199, v199, v195
	v_fmac_f32_e32 v194, v196, v201
	v_mul_f32_e32 v201, v199, v201
	s_and_saveexec_b64 s[28:29], s[10:11]
	v_mul_f32_e32 v203, v194, v198
	v_mul_f32_e32 v202, v201, v198
	v_add_f32_e32 v203, v203, v200
	ds_write_b64 v151, v[202:203] offset:53248
	s_or_b64 exec, exec, s[28:29]
	v_lshlrev_b32_e32 v209, 16, v225
	v_lshlrev_b32_e32 v207, 16, v226
	v_lshlrev_b32_e32 v206, 16, v227
	v_fmamk_f32 v30, v30, 0xbfb8aa3b, v242
	v_exp_f32_e32 v30, v30
	v_fmamk_f32 v31, v31, 0xbfb8aa3b, v242
	v_fmamk_f32 v34, v34, 0xbfb8aa3b, v243
	v_exp_f32_e32 v31, v31
	v_add_f32_e32 v30, 1.0, v30
	v_rcp_f32_e32 v30, v30
	v_exp_f32_e32 v34, v34
	v_add_f32_e32 v31, 1.0, v31
	v_rcp_f32_e32 v31, v31
	v_mul_f32_e32 v30, v229, v30
	v_add_f32_e32 v198, 1.0, v34
	v_exp_f32_e32 v34, v30
	v_rcp_f32_e32 v30, v198
	v_fmamk_f32 v35, v35, 0xbfb8aa3b, v243
	v_mul_f32_e32 v31, v229, v31
	v_fma_f32 v198, -v34, v34, 1.0
	v_sqrt_f32_e32 v198, v198
; template <bool PASS_C>
; DEVI void lru_item(const P& p, int item, int next_item, uint4& u0, uint4& u1, uint4& u2, float& cpre, char* smem) {
;     ...
; #pragma unroll
;     for (int nn = 0; nn < 4; ++nn) {
;         const int ch = 16 * nn + fr;
;         float uc[4];
; #pragma unroll
;         for (int j = 0; j < 4; ++j) {
;             const int tl = 16 * w + 4 * fq + j;
;             uc[j] = bf2f(*(const bf16_t*)(ucb + tl * 128 + ((((ch >> 3)) ^ (tl & 7)) << 4) + (ch & 7) * 2));
;         }
; #pragma unroll
;         for (int d = 0; d < 2; ++d) {
;             const float ba = prm[(5 + d) * 64 + ch], bx = prm[(7 + d) * 64 + ch], nsp8 = prm[(9 + d) * 64 + ch];
; #pragma unroll
;             for (int j = 0; j < 4; ++j) {
;                 const float r = __builtin_amdgcn_rcpf(1.0f + __builtin_amdgcn_exp2f(__builtin_fmaf(acc[(2 * d) * 4 + nn][j], -LOG2E, ba)));
;                 const float ig = __builtin_amdgcn_rcpf(1.0f + __builtin_amdgcn_exp2f(__builtin_fmaf(acc[(2 * d + 1) * 4 + nn][j], -LOG2E, bx)));
;                 const float a_ = __builtin_amdgcn_exp2f(nsp8 * r);
;                 av[nn][d][j] = a_;
;                 bv[nn][d][j] = __builtin_amdgcn_sqrtf(__builtin_fmaf(-a_, a_, 1.0f)) * ig * uc[j];
;             }
;             float A = 1.f, Bq = 0.f;
;             if (d == 0) {
; #pragma unroll
;                 for (int j = 0; j < 4; ++j) { Bq = av[nn][d][j] * Bq + bv[nn][d][j]; A *= av[nn][d][j]; }
;             } else {
; #pragma unroll
;                 for (int j = 3; j >= 0; --j) { Bq = av[nn][d][j] * Bq + bv[nn][d][j]; A *= av[nn][d][j]; }
;             }
;             float Ag[4], Bg[4];
;             rowgather4(A, Ag); rowgather4(Bq, Bg);
;             float AW = 1.f, BW = 0.f, AP = 1.f, BP = 0.f;
;             if (d == 0) {
; #pragma unroll
;                 for (int g = 0; g < 4; ++g) {
;                     if (g == fq) { AP = AW; BP = BW; }
;                     BW = Ag[g] * BW + Bg[g]; AW *= Ag[g];
;                 }
;             } else {
; #pragma unroll
;                 for (int g = 3; g >= 0; --g) {
;                     if (g == fq) { AP = AW; BP = BW; }
;                     BW = Ag[g] * BW + Bg[g]; AW *= Ag[g];
;                 }
;             }
;             apre[nn][d] = AP; bpre[nn][d] = BP;
;             if (fq == 0) { wagg[((w * 2 + d) * 64 + ch) * 2 + 0] = AW; wagg[((w * 2 + d) * 64 + ch) * 2 + 1] = BW; }
;         }
	v_exp_f32_e32 v35, v35
	v_exp_f32_e32 v31, v31
	v_fmamk_f32 v32, v32, 0xbfb8aa3b, v242
	v_exp_f32_e32 v32, v32
	v_mul_f32_e32 v30, v30, v198
	v_add_f32_e32 v35, 1.0, v35
	v_fma_f32 v198, -v31, v31, 1.0
	v_rcp_f32_e32 v35, v35
	v_sqrt_f32_e32 v198, v198
	v_add_f32_e32 v32, 1.0, v32
	v_rcp_f32_e32 v32, v32
	v_fmamk_f32 v33, v33, 0xbfb8aa3b, v242
	v_mul_f32_e32 v35, v35, v198
	v_exp_f32_e32 v198, v33
	v_mul_f32_e32 v32, v229, v32
	v_exp_f32_e32 v33, v32
	v_fmamk_f32 v36, v36, 0xbfb8aa3b, v243
	v_add_f32_e32 v32, 1.0, v198
	v_rcp_f32_e32 v32, v32
	v_fmamk_f32 v203, v37, 0xbfb8aa3b, v243
	v_exp_f32_e32 v200, v203
	v_exp_f32_e32 v36, v36
	v_mul_f32_e32 v32, v229, v32
	v_exp_f32_e32 v37, v32
	v_add_f32_e32 v32, 1.0, v200
	v_add_f32_e32 v36, 1.0, v36
	v_fma_f32 v198, -v33, v33, 1.0
	v_rcp_f32_e32 v200, v32
	v_fma_f32 v32, -v37, v37, 1.0
	v_rcp_f32_e32 v36, v36
	v_sqrt_f32_e32 v198, v198
	v_sqrt_f32_e32 v202, v32
	v_mul_f32_e32 v30, v30, v209
	v_mul_f32_e32 v32, v35, v207
	v_mul_f32_e32 v35, v36, v198
	v_mul_f32_e32 v36, v200, v202
	v_fma_f32 v200, 0, v34, v30
	v_lshlrev_b32_e32 v208, 16, v228
	v_mul_f32_e32 v35, v35, v206
	v_mul_f32_e32 v198, v34, v31
	v_fma_f32 v200, v31, v200, v32
	v_mul_f32_e32 v36, v36, v208
	v_mul_f32_e32 v198, v33, v198
	v_fma_f32 v200, v33, v200, v35
	v_mul_f32_e32 v198, v37, v198
	v_fma_f32 v200, v37, v200, v36
	v_mov_b32_e32 v204, v198
	v_mov_b32_e32 v202, v200
	s_nop 0
	v_permlane16_swap_b32_e32 v198, v204
	v_permlane16_swap_b32_e32 v200, v202
	v_mov_b32_e32 v205, v198
	v_mov_b32_e32 v203, v200
	s_nop 0
	v_permlane32_swap_b32_e32 v198, v205
	v_mov_b32_e32 v211, v204
	v_permlane32_swap_b32_e32 v200, v203
	v_mov_b32_e32 v212, v202
	v_permlane32_swap_b32_e32 v204, v211
	s_nop 0
	v_permlane32_swap_b32_e32 v202, v212
	v_fmac_f32_e32 v200, 0, v198
	v_fmac_f32_e32 v202, v200, v204
	v_mul_f32_e32 v204, v198, v204
	v_fmac_f32_e32 v203, v202, v205
	v_mul_f32_e32 v205, v204, v205
	s_and_saveexec_b64 s[28:29], s[10:11]
	v_mul_f32_e32 v213, v203, v211
	v_mul_f32_e32 v214, v205, v211
	v_add_f32_e32 v215, v213, v212
	ds_write_b64 v152, v[214:215] offset:52736
	s_or_b64 exec, exec, s[28:29]
	v_fmamk_f32 v22, v22, 0xbfb8aa3b, v244
	v_exp_f32_e32 v22, v22
	v_fmamk_f32 v23, v23, 0xbfb8aa3b, v244
	v_exp_f32_e32 v23, v23
	v_fmamk_f32 v26, v26, 0xbfb8aa3b, v245
	v_add_f32_e32 v22, 1.0, v22
	v_rcp_f32_e32 v22, v22
	v_add_f32_e32 v23, 1.0, v23
	v_exp_f32_e32 v26, v26
	v_rcp_f32_e32 v23, v23
	v_mul_f32_e32 v22, v231, v22
	v_exp_f32_e32 v22, v22
	v_fmamk_f32 v24, v24, 0xbfb8aa3b, v244
	v_fmamk_f32 v27, v27, 0xbfb8aa3b, v245
	v_add_f32_e32 v26, 1.0, v26
	v_mul_f32_e32 v23, v231, v23
	v_fma_f32 v213, -v22, v22, 1.0
	v_exp_f32_e32 v24, v24
	v_fmamk_f32 v25, v25, 0xbfb8aa3b, v244
	v_exp_f32_e32 v27, v27
	v_rcp_f32_e32 v26, v26
	v_exp_f32_e32 v23, v23
	v_sqrt_f32_e32 v213, v213
	v_exp_f32_e32 v25, v25
	v_add_f32_e32 v24, 1.0, v24
	v_add_f32_e32 v27, 1.0, v27
	v_fma_f32 v214, -v23, v23, 1.0
	v_mul_f32_e32 v26, v26, v213
	v_fmamk_f32 v28, v28, 0xbfb8aa3b, v245
	v_rcp_f32_e32 v24, v24
	v_add_f32_e32 v25, 1.0, v25
	v_rcp_f32_e32 v27, v27
	v_mul_f32_e32 v26, v26, v209
	v_sqrt_f32_e32 v209, v214
	v_exp_f32_e32 v28, v28
	v_rcp_f32_e32 v25, v25
	v_mul_f32_e32 v24, v231, v24
	v_fmamk_f32 v211, v29, 0xbfb8aa3b, v245
	v_mul_f32_e32 v209, v27, v209
	v_add_f32_e32 v27, 1.0, v28
	v_exp_f32_e32 v24, v24
	v_exp_f32_e32 v29, v211
	v_mul_f32_e32 v25, v231, v25
	v_rcp_f32_e32 v28, v27
	v_exp_f32_e32 v27, v25
	v_fma_f32 v210, -v24, v24, 1.0
	v_add_f32_e32 v25, 1.0, v29
	v_sqrt_f32_e32 v210, v210
	v_rcp_f32_e32 v29, v25
	v_fma_f32 v25, -v27, v27, 1.0
	v_sqrt_f32_e32 v211, v25
	v_mul_f32_e32 v28, v28, v210
	v_mul_f32_e32 v28, v28, v206
	v_mul_f32_e32 v206, v27, v24
	v_mul_f32_e32 v29, v29, v211
	v_mul_f32_e32 v29, v29, v208
	v_mul_f32_e32 v206, v23, v206
	v_mul_f32_e32 v212, v22, v206
	v_fma_f32 v206, 0, v27, v29
	v_mul_f32_e32 v25, v209, v207
	v_fma_f32 v206, v24, v206, v28
	v_fma_f32 v206, v23, v206, v25
	v_fma_f32 v213, v22, v206, v26
	v_mov_b32_e32 v211, v212
	v_mov_b32_e32 v207, v213
	s_nop 0
	v_permlane16_swap_b32_e32 v212, v211
	v_permlane16_swap_b32_e32 v213, v207
	v_mov_b32_e32 v206, v211
	v_mov_b32_e32 v209, v207
	v_mov_b32_e32 v210, v212
	v_permlane32_swap_b32_e32 v211, v206
	v_mov_b32_e32 v208, v213
	v_permlane32_swap_b32_e32 v207, v209
	v_permlane32_swap_b32_e32 v212, v210
	v_permlane32_swap_b32_e32 v213, v208
	v_fmac_f32_e32 v209, 0, v206
	v_fmac_f32_e32 v208, v209, v210
	v_mul_f32_e32 v210, v210, v206
	v_fmac_f32_e32 v207, v208, v211
	v_mul_f32_e32 v211, v210, v211
	s_and_saveexec_b64 s[28:29], s[10:11]
	v_mul_f32_e32 v214, v207, v212
	v_mul_f32_e32 v212, v211, v212
	v_add_f32_e32 v213, v214, v213
	ds_write_b64 v152, v[212:213] offset:53248
	s_or_b64 exec, exec, s[28:29]
	s_waitcnt lgkmcnt(0)
	s_barrier
; template <bool PASS_C>
; DEVI void lru_item(const P& p, int item, int next_item, uint4& u0, uint4& u1, uint4& u2, float& cpre, char* smem) {
;     ...
; #pragma unroll
;         for (int nn = 0; nn < 4; ++nn) {
;             const int ch = 16 * nn + fr;
;             float y[4];
;             {
;                 float hw = carry[ch];
; #pragma unroll
;                 for (int ww = 0; ww < 4; ++ww)
;                     if (ww < w) hw = wagg[((ww * 2 + 0) * 64 + ch) * 2] * hw + wagg[((ww * 2 + 0) * 64 + ch) * 2 + 1];
;                 float hh = apre[nn][0] * hw + bpre[nn][0];
; #pragma unroll
;                 for (int j = 0; j < 4; ++j) { hh = av[nn][0][j] * hh + bv[nn][0][j]; y[j] = hh; }
;             }
;             {
;                 float hw = carry[64 + ch];
; #pragma unroll
;     ...
;                     if (ww > w) hw = wagg[((ww * 2 + 1) * 64 + ch) * 2] * hw + wagg[((ww * 2 + 1) * 64 + ch) * 2 + 1];
;                 float hh = apre[nn][1] * hw + bpre[nn][1];
; #pragma unroll
;                 for (int j = 3; j >= 0; --j) { hh = av[nn][1][j] * hh + bv[nn][1][j]; y[j] += hh; }
;             }
; #pragma unroll
;             for (int j = 0; j < 4; ++j) ytile[(16 * w + 4 * fq + j) * 66 + ch] = y[j];
;         }
	ds_read_b32 v244, v122 offset:56832
	ds_read_b32 v245, v122 offset:57088
	ds_read_b64 v[232:233], v123 offset:52736
	ds_read_b64 v[234:235], v123 offset:53760
	ds_read_b64 v[236:237], v123 offset:54784
	ds_read_b64 v[238:239], v123 offset:56320
	ds_read_b64 v[240:241], v123 offset:55296
	ds_read_b64 v[242:243], v123 offset:54272
	ds_read_b32 v246, v122 offset:56896
	ds_read_b32 v247, v122 offset:57152
	ds_read_b64 v[218:219], v154 offset:52736
	ds_read_b64 v[220:221], v154 offset:53760
	ds_read_b64 v[222:223], v154 offset:54784
	ds_read_b64 v[224:225], v154 offset:56320
	ds_read_b64 v[226:227], v154 offset:55296
	ds_read_b64 v[228:229], v154 offset:54272
	s_waitcnt lgkmcnt(8)
	v_fma_f32 v248, v232, v244, v233
	v_cndmask_b32_e64 v212, v244, v248, s[4:5]
	v_fma_f32 v248, v234, v212, v235
	v_cndmask_b32_e64 v212, v212, v248, s[18:19]
	v_fma_f32 v248, v236, v212, v237
	v_cndmask_b32_e64 v212, v212, v248, s[20:21]
	v_fma_f32 v248, v238, v245, v239
	v_cndmask_b32_e64 v213, v245, v248, s[24:25]
	v_fma_f32 v248, v240, v213, v241
	v_cndmask_b32_e64 v213, v213, v248, s[8:9]
	v_fma_f32 v248, v242, v213, v243
	v_cndmask_b32_e64 v213, v213, v248, s[2:3]
	v_cndmask_b32_e64 v103, 1.0, v103, s[12:13]
	v_cndmask_b32_e64 v105, 0, v105, s[12:13]
	v_cndmask_b32_e64 v103, v103, v159, s[14:15]
	v_cndmask_b32_e64 v105, v105, v157, s[14:15]
	v_cndmask_b32_e64 v103, v103, v160, s[16:17]
	v_cndmask_b32_e64 v105, v105, v158, s[16:17]
	v_fmac_f32_e32 v105, v103, v212
	v_fmac_f32_e32 v87, v89, v105
	v_fmac_f32_e32 v93, v91, v87
	v_cndmask_b32_e64 v89, 1.0, v162, s[14:15]
	v_cndmask_b32_e64 v91, 0, v164, s[14:15]
	v_cndmask_b32_e64 v89, v89, v166, s[12:13]
	v_cndmask_b32_e64 v91, v91, v163, s[12:13]
	v_cndmask_b32_e64 v89, v89, v167, s[10:11]
	v_cndmask_b32_e64 v91, v91, v161, s[10:11]
	v_fmac_f32_e32 v91, v89, v213
	v_fmac_f32_e32 v77, v75, v91
	v_fmac_f32_e32 v76, v72, v77
	v_fmac_f32_e32 v73, v71, v76
	v_fmac_f32_e32 v97, v95, v93
	v_fmac_f32_e32 v74, v70, v73
	v_fmac_f32_e32 v99, v101, v97
	v_add_f32_e32 v71, v93, v73
	v_add_f32_e32 v73, v87, v74
	v_add_u32_e32 v70, 0x8c00, v153
	v_add_f32_e32 v75, v99, v77
	v_add_f32_e32 v72, v97, v76
	ds_write2_b32 v70, v73, v71 offset1:66
	ds_write2_b32 v70, v72, v75 offset0:132 offset1:198
	ds_read_b32 v244, v122 offset:56960
	ds_read_b32 v245, v122 offset:57216
	ds_read_b64 v[232:233], v155 offset:52736
	ds_read_b64 v[234:235], v155 offset:53760
	ds_read_b64 v[236:237], v155 offset:54784
	ds_read_b64 v[238:239], v155 offset:56320
	ds_read_b64 v[240:241], v155 offset:55296
	ds_read_b64 v[242:243], v155 offset:54272
	s_waitcnt lgkmcnt(10)
	v_fma_f32 v248, v218, v246, v219
	v_cndmask_b32_e64 v71, v246, v248, s[4:5]
	v_fma_f32 v248, v220, v71, v221
	v_cndmask_b32_e64 v71, v71, v248, s[18:19]
	v_fma_f32 v248, v222, v71, v223
	v_cndmask_b32_e64 v71, v71, v248, s[20:21]
	v_fma_f32 v248, v224, v247, v225
	v_cndmask_b32_e64 v72, v247, v248, s[24:25]
	v_fma_f32 v248, v226, v72, v227
	v_cndmask_b32_e64 v72, v72, v248, s[8:9]
	v_fma_f32 v248, v228, v72, v229
	v_cndmask_b32_e64 v72, v72, v248, s[2:3]
	v_cndmask_b32_e64 v73, 1.0, v165, s[12:13]
	v_cndmask_b32_e64 v74, 0, v168, s[12:13]
	v_cndmask_b32_e64 v73, v73, v171, s[14:15]
	v_cndmask_b32_e64 v74, v74, v169, s[14:15]
	v_cndmask_b32_e64 v73, v73, v173, s[16:17]
	v_cndmask_b32_e64 v74, v74, v170, s[16:17]
	v_fmac_f32_e32 v74, v73, v71
	v_fmac_f32_e32 v62, v66, v74
	v_fmac_f32_e32 v64, v63, v62
	v_fmac_f32_e32 v67, v65, v64
	v_cndmask_b32_e64 v63, 1.0, v183, s[14:15]
	v_cndmask_b32_e64 v65, 0, v185, s[14:15]
	v_cndmask_b32_e64 v63, v63, v187, s[12:13]
	v_cndmask_b32_e64 v65, v65, v184, s[12:13]
	v_cndmask_b32_e64 v63, v63, v188, s[10:11]
	v_cndmask_b32_e64 v65, v65, v177, s[10:11]
	v_fmac_f32_e32 v65, v63, v72
	v_fmac_f32_e32 v61, v59, v65
	v_fmac_f32_e32 v60, v56, v61
	v_fmac_f32_e32 v57, v55, v60
	v_fmac_f32_e32 v58, v54, v57
	v_fmac_f32_e32 v68, v69, v67
	v_add_f32_e32 v55, v64, v57
	v_add_f32_e32 v54, v62, v58
	v_add_f32_e32 v59, v68, v61
	v_add_f32_e32 v56, v67, v60
	ds_write2_b32 v70, v54, v55 offset0:16 offset1:82
	ds_write2_b32 v70, v56, v59 offset0:148 offset1:214
	ds_read_b32 v246, v122 offset:57024
	ds_read_b32 v247, v122 offset:57280
	ds_read_b64 v[218:219], v156 offset:52736
	ds_read_b64 v[220:221], v156 offset:53760
	ds_read_b64 v[222:223], v156 offset:54784
	ds_read_b64 v[224:225], v156 offset:56320
	ds_read_b64 v[226:227], v156 offset:55296
	ds_read_b64 v[228:229], v156 offset:54272
	s_waitcnt lgkmcnt(10)
	v_fma_f32 v248, v232, v244, v233
	v_cndmask_b32_e64 v54, v244, v248, s[4:5]
	v_fma_f32 v248, v234, v54, v235
	v_cndmask_b32_e64 v54, v54, v248, s[18:19]
	v_fma_f32 v248, v236, v54, v237
	v_cndmask_b32_e64 v54, v54, v248, s[20:21]
	v_fma_f32 v248, v238, v245, v239
	v_cndmask_b32_e64 v55, v245, v248, s[24:25]
	v_fma_f32 v248, v240, v55, v241
	v_cndmask_b32_e64 v55, v55, v248, s[8:9]
	v_fma_f32 v248, v242, v55, v243
	v_cndmask_b32_e64 v55, v55, v248, s[2:3]
	v_cndmask_b32_e64 v56, 1.0, v186, s[12:13]
	v_cndmask_b32_e64 v57, 0, v189, s[12:13]
	v_cndmask_b32_e64 v56, v56, v192, s[14:15]
	v_cndmask_b32_e64 v57, v57, v190, s[14:15]
	v_cndmask_b32_e64 v56, v56, v193, s[16:17]
	v_cndmask_b32_e64 v57, v57, v191, s[16:17]
	v_fmac_f32_e32 v57, v56, v54
	v_fmac_f32_e32 v46, v50, v57
	v_fmac_f32_e32 v48, v47, v46
	v_fmac_f32_e32 v51, v49, v48
	v_cndmask_b32_e64 v47, 1.0, v195, s[14:15]
	v_cndmask_b32_e64 v49, 0, v197, s[14:15]
	v_cndmask_b32_e64 v47, v47, v199, s[12:13]
	v_cndmask_b32_e64 v49, v49, v196, s[12:13]
	v_cndmask_b32_e64 v47, v47, v201, s[10:11]
	v_cndmask_b32_e64 v49, v49, v194, s[10:11]
	v_fmac_f32_e32 v49, v47, v55
	v_fmac_f32_e32 v45, v43, v49
	v_fmac_f32_e32 v44, v40, v45
	v_fmac_f32_e32 v41, v39, v44
	v_fmac_f32_e32 v42, v38, v41
	v_fmac_f32_e32 v52, v53, v51
	v_add_f32_e32 v39, v48, v41
	v_add_f32_e32 v38, v46, v42
	v_add_f32_e32 v43, v52, v45
	v_add_f32_e32 v40, v51, v44
	ds_write2_b32 v70, v38, v39 offset0:32 offset1:98
	ds_write2_b32 v70, v40, v43 offset0:164 offset1:230
	s_waitcnt lgkmcnt(2)
	v_fma_f32 v248, v218, v246, v219
	v_cndmask_b32_e64 v38, v246, v248, s[4:5]
	v_fma_f32 v248, v220, v38, v221
	v_cndmask_b32_e64 v38, v38, v248, s[18:19]
	v_fma_f32 v248, v222, v38, v223
	v_cndmask_b32_e64 v38, v38, v248, s[20:21]
	v_fma_f32 v248, v224, v247, v225
	v_cndmask_b32_e64 v39, v247, v248, s[24:25]
	v_fma_f32 v248, v226, v39, v227
	v_cndmask_b32_e64 v39, v39, v248, s[8:9]
	v_fma_f32 v248, v228, v39, v229
	v_cndmask_b32_e64 v39, v39, v248, s[2:3]
	s_branch .LBB0_720
